# MFMA order: accumulate chains of 2 with the accumulators walked in snake order over (m,n), so consecutive chains share one operand register group
# speedup vs baseline: 1.0175x; 1.0046x over previous
.LBB0_177:
	s_ashr_i32 s29, s28, 31
	s_lshl_b64 s[38:39], s[28:29], 19
	s_add_u32 s38, s84, s38
	s_addc_u32 s39, s85, s39
	s_and_b64 s[40:41], s[36:37], exec
	s_cselect_b32 s29, s39, s1
	s_cselect_b32 s62, s38, s0
	s_ashr_i32 s35, s34, 31
	s_lshl_b64 s[40:41], s[34:35], 19
	s_add_u32 s40, s16, s40
	s_addc_u32 s41, s17, s41
	s_and_b64 s[46:47], s[36:37], exec
	s_cselect_b32 s63, s41, s45
	s_cselect_b32 s64, s40, s44
	s_lshl_b32 s35, s30, 8
	s_add_u32 s65, s44, 0x100
	v_mov_b32_e32 v2, 0
	v_or_b32_e32 v134, s35, v172
	v_lshl_add_u64 v[130:131], s[0:1], 0, v[148:149]
	v_lshl_add_u64 v[132:133], s[0:1], 0, v[150:151]
	s_addc_u32 s66, s45, 0
	s_mov_b32 s67, -2
	s_mov_b64 s[30:31], 0
	s_waitcnt lgkmcnt(0)
	ds_read_b128 v[160:163], v240
	ds_read_b128 v[164:167], v240 offset:1024
	ds_read_b128 v[178:181], v240 offset:2048
	ds_read_b128 v[182:185], v240 offset:3072
	s_add_u32 s44, s0, s30
	ds_read_b128 v[186:189], v240 offset:16384
	ds_read_b128 v[190:193], v240 offset:17408
	ds_read_b128 v[194:197], v240 offset:18432
	ds_read_b128 v[198:201], v240 offset:19456
	s_addc_u32 s45, s1, s31
	s_add_u32 s44, s44, 0x100
	s_addc_u32 s45, s45, 0
	s_add_u32 s72, s65, s30
	s_addc_u32 s73, s66, s31
	s_cmpk_eq_i32 s30, 0x700
	s_cselect_b32 s47, s29, s45
	s_cselect_b32 s46, s62, s44
	s_cselect_b32 s45, s63, s73
	s_cselect_b32 s44, s64, s72
	s_add_u32 s90, s0, s30
	s_addc_u32 s91, s1, s31
	s_add_i32 m0, s43, 0xc000
	ds_read_b128 v[202:205], v176
	ds_read_b128 v[206:209], v176 offset:1024
	ds_read_b128 v[210:213], v176 offset:2048
	ds_read_b128 v[214:217], v176 offset:3072
	ds_read_b128 v[218:221], v176 offset:4096
	ds_read_b128 v[222:225], v176 offset:5120
	ds_read_b128 v[226:229], v176 offset:6144
	ds_read_b128 v[230:233], v176 offset:7168
	global_load_lds_dwordx4 v148, s[90:91]
	s_add_i32 m0, s43, 0xe000
	s_nop 0
	global_load_lds_dwordx4 v150, s[90:91]
	s_waitcnt vmcnt(8)
	s_waitcnt lgkmcnt(0)
	s_barrier
	s_setprio 1
	v_mfma_f32_16x16x32_bf16 v[126:129], v[160:163], v[202:205], 0
	v_mfma_f32_16x16x32_bf16 v[126:129], v[164:167], v[206:209], v[126:129]
	v_mfma_f32_16x16x32_bf16 v[122:125], v[178:181], v[202:205], 0
	v_mfma_f32_16x16x32_bf16 v[122:125], v[182:185], v[206:209], v[122:125]
	v_mfma_f32_16x16x32_bf16 v[106:109], v[178:181], v[210:213], 0
	v_mfma_f32_16x16x32_bf16 v[106:109], v[182:185], v[214:217], v[106:109]
	v_mfma_f32_16x16x32_bf16 v[110:113], v[160:163], v[210:213], 0
	v_mfma_f32_16x16x32_bf16 v[110:113], v[164:167], v[214:217], v[110:113]
	v_mfma_f32_16x16x32_bf16 v[94:97], v[160:163], v[218:221], 0
	v_mfma_f32_16x16x32_bf16 v[94:97], v[164:167], v[222:225], v[94:97]
	v_mfma_f32_16x16x32_bf16 v[90:93], v[178:181], v[218:221], 0
	v_mfma_f32_16x16x32_bf16 v[90:93], v[182:185], v[222:225], v[90:93]
	v_mfma_f32_16x16x32_bf16 v[74:77], v[178:181], v[226:229], 0
	v_mfma_f32_16x16x32_bf16 v[74:77], v[182:185], v[230:233], v[74:77]
	v_mfma_f32_16x16x32_bf16 v[78:81], v[160:163], v[226:229], 0
	v_mfma_f32_16x16x32_bf16 v[78:81], v[164:167], v[230:233], v[78:81]
	v_mfma_f32_16x16x32_bf16 v[118:121], v[186:189], v[202:205], 0
	v_mfma_f32_16x16x32_bf16 v[118:121], v[190:193], v[206:209], v[118:121]
	v_mfma_f32_16x16x32_bf16 v[114:117], v[194:197], v[202:205], 0
	v_mfma_f32_16x16x32_bf16 v[114:117], v[198:201], v[206:209], v[114:117]
	v_mfma_f32_16x16x32_bf16 v[98:101], v[194:197], v[210:213], 0
	v_mfma_f32_16x16x32_bf16 v[98:101], v[198:201], v[214:217], v[98:101]
	v_mfma_f32_16x16x32_bf16 v[102:105], v[186:189], v[210:213], 0
	v_mfma_f32_16x16x32_bf16 v[102:105], v[190:193], v[214:217], v[102:105]
	v_mfma_f32_16x16x32_bf16 v[86:89], v[186:189], v[218:221], 0
	v_mfma_f32_16x16x32_bf16 v[86:89], v[190:193], v[222:225], v[86:89]
	v_mfma_f32_16x16x32_bf16 v[82:85], v[194:197], v[218:221], 0
	v_mfma_f32_16x16x32_bf16 v[82:85], v[198:201], v[222:225], v[82:85]
	s_setprio 2
	s_barrier
	v_mfma_f32_16x16x32_bf16 v[66:69], v[194:197], v[226:229], 0
	v_mfma_f32_16x16x32_bf16 v[66:69], v[198:201], v[230:233], v[66:69]
	v_mfma_f32_16x16x32_bf16 v[70:73], v[186:189], v[226:229], 0
	v_mfma_f32_16x16x32_bf16 v[70:73], v[190:193], v[230:233], v[70:73]
	s_setprio 0
	s_nop 0
	s_add_i32 s72, s60, s33
	s_mov_b32 m0, s72
	ds_read_b128 v[202:205], v176 offset:16384
	ds_read_b128 v[206:209], v176 offset:17408
	ds_read_b128 v[210:213], v176 offset:18432
	ds_read_b128 v[214:217], v176 offset:19456
	ds_read_b128 v[218:221], v176 offset:20480
	ds_read_b128 v[222:225], v176 offset:21504
	ds_read_b128 v[226:229], v176 offset:22528
	ds_read_b128 v[230:233], v176 offset:23552
	global_load_lds_dwordx4 v140, s[44:45]
	s_add_i32 m0, s72, 0x2000
	s_add_u32 s72, s44, 0x40000
	s_addc_u32 s73, s45, 0
	s_add_i32 s74, s61, s33
	global_load_lds_dwordx4 v144, s[44:45]
	s_mov_b32 m0, s74
	s_add_u32 s94, s46, 0x80
	s_addc_u32 s95, s47, 0
	global_load_lds_dwordx4 v140, s[72:73]
	s_add_i32 m0, s74, 0x2000
	s_nop 0
	global_load_lds_dwordx4 v144, s[72:73]
	s_mov_b32 m0, s43
	s_nop 0
	global_load_lds_dwordx4 v138, s[46:47]
	s_mov_b32 m0, s54
	s_nop 0
	global_load_lds_dwordx4 v142, s[46:47]
	s_waitcnt vmcnt(8)
	s_waitcnt lgkmcnt(0)
	s_barrier
	s_setprio 1
	v_mfma_f32_16x16x32_bf16 v[62:65], v[160:163], v[202:205], 0
	v_mfma_f32_16x16x32_bf16 v[62:65], v[164:167], v[206:209], v[62:65]
	v_mfma_f32_16x16x32_bf16 v[58:61], v[178:181], v[202:205], 0
	v_mfma_f32_16x16x32_bf16 v[58:61], v[182:185], v[206:209], v[58:61]
	v_mfma_f32_16x16x32_bf16 v[42:45], v[178:181], v[210:213], 0
	v_mfma_f32_16x16x32_bf16 v[42:45], v[182:185], v[214:217], v[42:45]
	v_mfma_f32_16x16x32_bf16 v[46:49], v[160:163], v[210:213], 0
	v_mfma_f32_16x16x32_bf16 v[46:49], v[164:167], v[214:217], v[46:49]
	v_mfma_f32_16x16x32_bf16 v[30:33], v[160:163], v[218:221], 0
	v_mfma_f32_16x16x32_bf16 v[30:33], v[164:167], v[222:225], v[30:33]
	v_mfma_f32_16x16x32_bf16 v[26:29], v[178:181], v[218:221], 0
	v_mfma_f32_16x16x32_bf16 v[26:29], v[182:185], v[222:225], v[26:29]
	v_mfma_f32_16x16x32_bf16 v[10:13], v[178:181], v[226:229], 0
	v_mfma_f32_16x16x32_bf16 v[10:13], v[182:185], v[230:233], v[10:13]
	v_mfma_f32_16x16x32_bf16 v[14:17], v[160:163], v[226:229], 0
	v_mfma_f32_16x16x32_bf16 v[14:17], v[164:167], v[230:233], v[14:17]
	v_mfma_f32_16x16x32_bf16 v[54:57], v[186:189], v[202:205], 0
	v_mfma_f32_16x16x32_bf16 v[54:57], v[190:193], v[206:209], v[54:57]
	v_mfma_f32_16x16x32_bf16 v[50:53], v[194:197], v[202:205], 0
	v_mfma_f32_16x16x32_bf16 v[50:53], v[198:201], v[206:209], v[50:53]
	v_mfma_f32_16x16x32_bf16 v[34:37], v[194:197], v[210:213], 0
	v_mfma_f32_16x16x32_bf16 v[34:37], v[198:201], v[214:217], v[34:37]
	v_mfma_f32_16x16x32_bf16 v[38:41], v[186:189], v[210:213], 0
	v_mfma_f32_16x16x32_bf16 v[38:41], v[190:193], v[214:217], v[38:41]
	v_mfma_f32_16x16x32_bf16 v[22:25], v[186:189], v[218:221], 0
	v_mfma_f32_16x16x32_bf16 v[22:25], v[190:193], v[222:225], v[22:25]
	v_mfma_f32_16x16x32_bf16 v[18:21], v[194:197], v[218:221], 0
	v_mfma_f32_16x16x32_bf16 v[18:21], v[198:201], v[222:225], v[18:21]
	s_setprio 2
	s_barrier
	v_mfma_f32_16x16x32_bf16 v[2:5], v[194:197], v[226:229], 0
	v_mfma_f32_16x16x32_bf16 v[2:5], v[198:201], v[230:233], v[2:5]
	v_mfma_f32_16x16x32_bf16 v[6:9], v[186:189], v[226:229], 0
	v_mfma_f32_16x16x32_bf16 v[6:9], v[190:193], v[230:233], v[6:9]
	s_setprio 0
	s_nop 0
	s_add_i32 s72, 0, 0x18000
	s_add_i32 s73, 0, 0x1c000
	ds_read_b128 v[160:163], v240 offset:32768
	ds_read_b128 v[164:167], v240 offset:33792
	ds_read_b128 v[178:181], v240 offset:34816
	ds_read_b128 v[182:185], v240 offset:35840
	ds_read_b128 v[186:189], v240 offset:49152
	ds_read_b128 v[190:193], v240 offset:50176
	ds_read_b128 v[194:197], v240 offset:51200
	ds_read_b128 v[198:201], v240 offset:52224
	s_add_u32 s46, s46, 0x40000
	s_addc_u32 s47, s47, 0
	s_mov_b32 m0, s55
	ds_read_b128 v[202:205], v176 offset:32768
	ds_read_b128 v[206:209], v176 offset:33792
	ds_read_b128 v[210:213], v176 offset:34816
	ds_read_b128 v[214:217], v176 offset:35840
	ds_read_b128 v[218:221], v176 offset:36864
	ds_read_b128 v[222:225], v176 offset:37888
	ds_read_b128 v[226:229], v176 offset:38912
	ds_read_b128 v[230:233], v176 offset:39936
	global_load_lds_dwordx4 v138, s[46:47]
	s_mov_b32 m0, s56
	s_nop 0
	global_load_lds_dwordx4 v142, s[46:47]
	s_waitcnt vmcnt(8)
	s_waitcnt lgkmcnt(0)
	s_barrier
	s_setprio 1
	v_mfma_f32_16x16x32_bf16 v[126:129], v[160:163], v[202:205], v[126:129]
	v_mfma_f32_16x16x32_bf16 v[126:129], v[164:167], v[206:209], v[126:129]
	v_mfma_f32_16x16x32_bf16 v[122:125], v[178:181], v[202:205], v[122:125]
	v_mfma_f32_16x16x32_bf16 v[122:125], v[182:185], v[206:209], v[122:125]
	v_mfma_f32_16x16x32_bf16 v[106:109], v[178:181], v[210:213], v[106:109]
	v_mfma_f32_16x16x32_bf16 v[106:109], v[182:185], v[214:217], v[106:109]
	v_mfma_f32_16x16x32_bf16 v[110:113], v[160:163], v[210:213], v[110:113]
	v_mfma_f32_16x16x32_bf16 v[110:113], v[164:167], v[214:217], v[110:113]
	v_mfma_f32_16x16x32_bf16 v[94:97], v[160:163], v[218:221], v[94:97]
	v_mfma_f32_16x16x32_bf16 v[94:97], v[164:167], v[222:225], v[94:97]
	v_mfma_f32_16x16x32_bf16 v[90:93], v[178:181], v[218:221], v[90:93]
	v_mfma_f32_16x16x32_bf16 v[90:93], v[182:185], v[222:225], v[90:93]
	v_mfma_f32_16x16x32_bf16 v[74:77], v[178:181], v[226:229], v[74:77]
	v_mfma_f32_16x16x32_bf16 v[74:77], v[182:185], v[230:233], v[74:77]
	v_mfma_f32_16x16x32_bf16 v[78:81], v[160:163], v[226:229], v[78:81]
	v_mfma_f32_16x16x32_bf16 v[78:81], v[164:167], v[230:233], v[78:81]
	v_mfma_f32_16x16x32_bf16 v[118:121], v[186:189], v[202:205], v[118:121]
	v_mfma_f32_16x16x32_bf16 v[118:121], v[190:193], v[206:209], v[118:121]
	v_mfma_f32_16x16x32_bf16 v[114:117], v[194:197], v[202:205], v[114:117]
	v_mfma_f32_16x16x32_bf16 v[114:117], v[198:201], v[206:209], v[114:117]
	v_mfma_f32_16x16x32_bf16 v[98:101], v[194:197], v[210:213], v[98:101]
	v_mfma_f32_16x16x32_bf16 v[98:101], v[198:201], v[214:217], v[98:101]
	v_mfma_f32_16x16x32_bf16 v[102:105], v[186:189], v[210:213], v[102:105]
	v_mfma_f32_16x16x32_bf16 v[102:105], v[190:193], v[214:217], v[102:105]
	v_mfma_f32_16x16x32_bf16 v[86:89], v[186:189], v[218:221], v[86:89]
	v_mfma_f32_16x16x32_bf16 v[86:89], v[190:193], v[222:225], v[86:89]
	v_mfma_f32_16x16x32_bf16 v[82:85], v[194:197], v[218:221], v[82:85]
	v_mfma_f32_16x16x32_bf16 v[82:85], v[198:201], v[222:225], v[82:85]
	s_setprio 2
	s_barrier
	v_mfma_f32_16x16x32_bf16 v[66:69], v[194:197], v[226:229], v[66:69]
	v_mfma_f32_16x16x32_bf16 v[66:69], v[198:201], v[230:233], v[66:69]
	v_mfma_f32_16x16x32_bf16 v[70:73], v[186:189], v[226:229], v[70:73]
	v_mfma_f32_16x16x32_bf16 v[70:73], v[190:193], v[230:233], v[70:73]
	s_setprio 0
	s_nop 0
	s_add_i32 s46, s72, s33
	s_add_u32 s96, s44, 0x80
	s_addc_u32 s97, s45, 0
	s_mov_b32 m0, s46
	ds_read_b128 v[202:205], v176 offset:49152
	ds_read_b128 v[206:209], v176 offset:50176
	ds_read_b128 v[210:213], v176 offset:51200
	ds_read_b128 v[214:217], v176 offset:52224
	ds_read_b128 v[218:221], v176 offset:53248
	ds_read_b128 v[222:225], v176 offset:54272
	ds_read_b128 v[226:229], v176 offset:55296
	ds_read_b128 v[230:233], v176 offset:56320
	global_load_lds_dwordx4 v140, s[96:97]
	s_add_i32 m0, s46, 0x2000
	s_add_u32 s44, s44, 0x40080
	s_addc_u32 s45, s45, 0
	s_add_i32 s46, s73, s33
	global_load_lds_dwordx4 v144, s[96:97]
	s_mov_b32 m0, s46
	s_nop 0
	global_load_lds_dwordx4 v140, s[44:45]
	s_add_i32 m0, s46, 0x2000
	s_nop 0
	global_load_lds_dwordx4 v144, s[44:45]
	s_mov_b32 m0, s57
	s_nop 0
	global_load_lds_dwordx4 v138, s[94:95]
	s_mov_b32 m0, s58
	s_nop 0
	global_load_lds_dwordx4 v142, s[94:95]
	s_waitcnt vmcnt(8)
	s_waitcnt lgkmcnt(0)
	s_barrier
	s_setprio 1
	v_mfma_f32_16x16x32_bf16 v[62:65], v[160:163], v[202:205], v[62:65]
	v_mfma_f32_16x16x32_bf16 v[62:65], v[164:167], v[206:209], v[62:65]
	v_mfma_f32_16x16x32_bf16 v[58:61], v[178:181], v[202:205], v[58:61]
	v_mfma_f32_16x16x32_bf16 v[58:61], v[182:185], v[206:209], v[58:61]
	v_mfma_f32_16x16x32_bf16 v[42:45], v[178:181], v[210:213], v[42:45]
	v_mfma_f32_16x16x32_bf16 v[42:45], v[182:185], v[214:217], v[42:45]
	v_mfma_f32_16x16x32_bf16 v[46:49], v[160:163], v[210:213], v[46:49]
	v_mfma_f32_16x16x32_bf16 v[46:49], v[164:167], v[214:217], v[46:49]
	v_mfma_f32_16x16x32_bf16 v[30:33], v[160:163], v[218:221], v[30:33]
	v_mfma_f32_16x16x32_bf16 v[30:33], v[164:167], v[222:225], v[30:33]
	v_mfma_f32_16x16x32_bf16 v[26:29], v[178:181], v[218:221], v[26:29]
	v_mfma_f32_16x16x32_bf16 v[26:29], v[182:185], v[222:225], v[26:29]
	v_mfma_f32_16x16x32_bf16 v[10:13], v[178:181], v[226:229], v[10:13]
	v_mfma_f32_16x16x32_bf16 v[10:13], v[182:185], v[230:233], v[10:13]
	v_mfma_f32_16x16x32_bf16 v[14:17], v[160:163], v[226:229], v[14:17]
	v_mfma_f32_16x16x32_bf16 v[14:17], v[164:167], v[230:233], v[14:17]
	v_mfma_f32_16x16x32_bf16 v[54:57], v[186:189], v[202:205], v[54:57]
	v_mfma_f32_16x16x32_bf16 v[54:57], v[190:193], v[206:209], v[54:57]
	v_mfma_f32_16x16x32_bf16 v[50:53], v[194:197], v[202:205], v[50:53]
	v_mfma_f32_16x16x32_bf16 v[50:53], v[198:201], v[206:209], v[50:53]
	v_mfma_f32_16x16x32_bf16 v[34:37], v[194:197], v[210:213], v[34:37]
	v_mfma_f32_16x16x32_bf16 v[34:37], v[198:201], v[214:217], v[34:37]
	v_mfma_f32_16x16x32_bf16 v[38:41], v[186:189], v[210:213], v[38:41]
	v_mfma_f32_16x16x32_bf16 v[38:41], v[190:193], v[214:217], v[38:41]
	v_mfma_f32_16x16x32_bf16 v[22:25], v[186:189], v[218:221], v[22:25]
	v_mfma_f32_16x16x32_bf16 v[22:25], v[190:193], v[222:225], v[22:25]
	v_mfma_f32_16x16x32_bf16 v[18:21], v[194:197], v[218:221], v[18:21]
	v_mfma_f32_16x16x32_bf16 v[18:21], v[198:201], v[222:225], v[18:21]
	s_setprio 2
	s_barrier
	v_mfma_f32_16x16x32_bf16 v[2:5], v[194:197], v[226:229], v[2:5]
	v_mfma_f32_16x16x32_bf16 v[2:5], v[198:201], v[230:233], v[2:5]
	v_mfma_f32_16x16x32_bf16 v[6:9], v[186:189], v[226:229], v[6:9]
	v_mfma_f32_16x16x32_bf16 v[6:9], v[190:193], v[230:233], v[6:9]
	s_setprio 0
	s_nop 0
	s_add_i32 s67, s67, 2
	s_add_u32 s30, s30, 0x100
	s_addc_u32 s31, s31, 0
	s_cmp_gt_u32 s67, 13
	s_cbranch_scc1 .LBB0_181
	s_branch .LBB0_179
.LBB0_178:
	s_waitcnt lgkmcnt(0)
	ds_read_b128 v[160:163], v240
	ds_read_b128 v[164:167], v240 offset:1024
	ds_read_b128 v[178:181], v240 offset:2048
	ds_read_b128 v[182:185], v240 offset:3072
	s_add_u32 s44, s0, s30
	ds_read_b128 v[186:189], v240 offset:16384
	ds_read_b128 v[190:193], v240 offset:17408
	ds_read_b128 v[194:197], v240 offset:18432
	ds_read_b128 v[198:201], v240 offset:19456
	s_addc_u32 s45, s1, s31
	s_add_u32 s44, s44, 0x100
	s_addc_u32 s45, s45, 0
	s_add_u32 s72, s65, s30
	s_addc_u32 s73, s66, s31
	s_cmpk_eq_i32 s30, 0x700
	s_cselect_b32 s47, s29, s45
	s_cselect_b32 s46, s62, s44
	s_cselect_b32 s45, s63, s73
	s_cselect_b32 s44, s64, s72
	s_add_u32 s90, s0, s30
	s_addc_u32 s91, s1, s31
	s_add_i32 m0, s43, 0xc000
	ds_read_b128 v[202:205], v176
	ds_read_b128 v[206:209], v176 offset:1024
	ds_read_b128 v[210:213], v176 offset:2048
	ds_read_b128 v[214:217], v176 offset:3072
	ds_read_b128 v[218:221], v176 offset:4096
	ds_read_b128 v[222:225], v176 offset:5120
	ds_read_b128 v[226:229], v176 offset:6144
	ds_read_b128 v[230:233], v176 offset:7168
	global_load_lds_dwordx4 v148, s[90:91]
	s_add_i32 m0, s43, 0xe000
	s_nop 0
	global_load_lds_dwordx4 v150, s[90:91]
	s_waitcnt vmcnt(8)
	s_waitcnt lgkmcnt(0)
	s_barrier
	s_setprio 1
	v_mfma_f32_16x16x32_bf16 v[126:129], v[160:163], v[202:205], v[126:129]
	v_mfma_f32_16x16x32_bf16 v[126:129], v[164:167], v[206:209], v[126:129]
	v_mfma_f32_16x16x32_bf16 v[122:125], v[178:181], v[202:205], v[122:125]
	v_mfma_f32_16x16x32_bf16 v[122:125], v[182:185], v[206:209], v[122:125]
	v_mfma_f32_16x16x32_bf16 v[106:109], v[178:181], v[210:213], v[106:109]
	v_mfma_f32_16x16x32_bf16 v[106:109], v[182:185], v[214:217], v[106:109]
	v_mfma_f32_16x16x32_bf16 v[110:113], v[160:163], v[210:213], v[110:113]
	v_mfma_f32_16x16x32_bf16 v[110:113], v[164:167], v[214:217], v[110:113]
	v_mfma_f32_16x16x32_bf16 v[94:97], v[160:163], v[218:221], v[94:97]
	v_mfma_f32_16x16x32_bf16 v[94:97], v[164:167], v[222:225], v[94:97]
	v_mfma_f32_16x16x32_bf16 v[90:93], v[178:181], v[218:221], v[90:93]
	v_mfma_f32_16x16x32_bf16 v[90:93], v[182:185], v[222:225], v[90:93]
	v_mfma_f32_16x16x32_bf16 v[74:77], v[178:181], v[226:229], v[74:77]
	v_mfma_f32_16x16x32_bf16 v[74:77], v[182:185], v[230:233], v[74:77]
	v_mfma_f32_16x16x32_bf16 v[78:81], v[160:163], v[226:229], v[78:81]
	v_mfma_f32_16x16x32_bf16 v[78:81], v[164:167], v[230:233], v[78:81]
	v_mfma_f32_16x16x32_bf16 v[118:121], v[186:189], v[202:205], v[118:121]
	v_mfma_f32_16x16x32_bf16 v[118:121], v[190:193], v[206:209], v[118:121]
	v_mfma_f32_16x16x32_bf16 v[114:117], v[194:197], v[202:205], v[114:117]
	v_mfma_f32_16x16x32_bf16 v[114:117], v[198:201], v[206:209], v[114:117]
	v_mfma_f32_16x16x32_bf16 v[98:101], v[194:197], v[210:213], v[98:101]
	v_mfma_f32_16x16x32_bf16 v[98:101], v[198:201], v[214:217], v[98:101]
	v_mfma_f32_16x16x32_bf16 v[102:105], v[186:189], v[210:213], v[102:105]
	v_mfma_f32_16x16x32_bf16 v[102:105], v[190:193], v[214:217], v[102:105]
	v_mfma_f32_16x16x32_bf16 v[86:89], v[186:189], v[218:221], v[86:89]
	v_mfma_f32_16x16x32_bf16 v[86:89], v[190:193], v[222:225], v[86:89]
	v_mfma_f32_16x16x32_bf16 v[82:85], v[194:197], v[218:221], v[82:85]
	v_mfma_f32_16x16x32_bf16 v[82:85], v[198:201], v[222:225], v[82:85]
	s_setprio 2
	s_barrier
	v_mfma_f32_16x16x32_bf16 v[66:69], v[194:197], v[226:229], v[66:69]
	v_mfma_f32_16x16x32_bf16 v[66:69], v[198:201], v[230:233], v[66:69]
	v_mfma_f32_16x16x32_bf16 v[70:73], v[186:189], v[226:229], v[70:73]
	v_mfma_f32_16x16x32_bf16 v[70:73], v[190:193], v[230:233], v[70:73]
	s_setprio 0
	s_nop 0
	s_add_i32 s72, s60, s33
	s_mov_b32 m0, s72
	ds_read_b128 v[202:205], v176 offset:16384
	ds_read_b128 v[206:209], v176 offset:17408
	ds_read_b128 v[210:213], v176 offset:18432
	ds_read_b128 v[214:217], v176 offset:19456
	ds_read_b128 v[218:221], v176 offset:20480
	ds_read_b128 v[222:225], v176 offset:21504
	ds_read_b128 v[226:229], v176 offset:22528
	ds_read_b128 v[230:233], v176 offset:23552
	global_load_lds_dwordx4 v140, s[44:45]
	s_add_i32 m0, s72, 0x2000
	s_add_u32 s72, s44, 0x40000
	s_addc_u32 s73, s45, 0
	s_add_i32 s74, s61, s33
	global_load_lds_dwordx4 v144, s[44:45]
	s_mov_b32 m0, s74
	s_add_u32 s94, s46, 0x80
	s_addc_u32 s95, s47, 0
	global_load_lds_dwordx4 v140, s[72:73]
	s_add_i32 m0, s74, 0x2000
	s_nop 0
	global_load_lds_dwordx4 v144, s[72:73]
	s_mov_b32 m0, s43
	s_nop 0
	global_load_lds_dwordx4 v138, s[46:47]
	s_mov_b32 m0, s54
	s_nop 0
	global_load_lds_dwordx4 v142, s[46:47]
	s_waitcnt vmcnt(8)
	s_waitcnt lgkmcnt(0)
	s_barrier
	s_setprio 1
	v_mfma_f32_16x16x32_bf16 v[62:65], v[160:163], v[202:205], v[62:65]
	v_mfma_f32_16x16x32_bf16 v[62:65], v[164:167], v[206:209], v[62:65]
	v_mfma_f32_16x16x32_bf16 v[58:61], v[178:181], v[202:205], v[58:61]
	v_mfma_f32_16x16x32_bf16 v[58:61], v[182:185], v[206:209], v[58:61]
	v_mfma_f32_16x16x32_bf16 v[42:45], v[178:181], v[210:213], v[42:45]
	v_mfma_f32_16x16x32_bf16 v[42:45], v[182:185], v[214:217], v[42:45]
	v_mfma_f32_16x16x32_bf16 v[46:49], v[160:163], v[210:213], v[46:49]
	v_mfma_f32_16x16x32_bf16 v[46:49], v[164:167], v[214:217], v[46:49]
	v_mfma_f32_16x16x32_bf16 v[30:33], v[160:163], v[218:221], v[30:33]
	v_mfma_f32_16x16x32_bf16 v[30:33], v[164:167], v[222:225], v[30:33]
	v_mfma_f32_16x16x32_bf16 v[26:29], v[178:181], v[218:221], v[26:29]
	v_mfma_f32_16x16x32_bf16 v[26:29], v[182:185], v[222:225], v[26:29]
	v_mfma_f32_16x16x32_bf16 v[10:13], v[178:181], v[226:229], v[10:13]
	v_mfma_f32_16x16x32_bf16 v[10:13], v[182:185], v[230:233], v[10:13]
	v_mfma_f32_16x16x32_bf16 v[14:17], v[160:163], v[226:229], v[14:17]
	v_mfma_f32_16x16x32_bf16 v[14:17], v[164:167], v[230:233], v[14:17]
	v_mfma_f32_16x16x32_bf16 v[54:57], v[186:189], v[202:205], v[54:57]
	v_mfma_f32_16x16x32_bf16 v[54:57], v[190:193], v[206:209], v[54:57]
	v_mfma_f32_16x16x32_bf16 v[50:53], v[194:197], v[202:205], v[50:53]
	v_mfma_f32_16x16x32_bf16 v[50:53], v[198:201], v[206:209], v[50:53]
	v_mfma_f32_16x16x32_bf16 v[34:37], v[194:197], v[210:213], v[34:37]
	v_mfma_f32_16x16x32_bf16 v[34:37], v[198:201], v[214:217], v[34:37]
	v_mfma_f32_16x16x32_bf16 v[38:41], v[186:189], v[210:213], v[38:41]
	v_mfma_f32_16x16x32_bf16 v[38:41], v[190:193], v[214:217], v[38:41]
	v_mfma_f32_16x16x32_bf16 v[22:25], v[186:189], v[218:221], v[22:25]
	v_mfma_f32_16x16x32_bf16 v[22:25], v[190:193], v[222:225], v[22:25]
	v_mfma_f32_16x16x32_bf16 v[18:21], v[194:197], v[218:221], v[18:21]
	v_mfma_f32_16x16x32_bf16 v[18:21], v[198:201], v[222:225], v[18:21]
	s_setprio 2
	s_barrier
	v_mfma_f32_16x16x32_bf16 v[2:5], v[194:197], v[226:229], v[2:5]
	v_mfma_f32_16x16x32_bf16 v[2:5], v[198:201], v[230:233], v[2:5]
	v_mfma_f32_16x16x32_bf16 v[6:9], v[186:189], v[226:229], v[6:9]
	v_mfma_f32_16x16x32_bf16 v[6:9], v[190:193], v[230:233], v[6:9]
	s_setprio 0
	s_nop 0
	s_add_i32 s72, 0, 0x18000
	s_add_i32 s73, 0, 0x1c000
	ds_read_b128 v[160:163], v240 offset:32768
	ds_read_b128 v[164:167], v240 offset:33792
	ds_read_b128 v[178:181], v240 offset:34816
	ds_read_b128 v[182:185], v240 offset:35840
	ds_read_b128 v[186:189], v240 offset:49152
	ds_read_b128 v[190:193], v240 offset:50176
	ds_read_b128 v[194:197], v240 offset:51200
	ds_read_b128 v[198:201], v240 offset:52224
	s_add_u32 s46, s46, 0x40000
	s_addc_u32 s47, s47, 0
	s_mov_b32 m0, s55
	ds_read_b128 v[202:205], v176 offset:32768
	ds_read_b128 v[206:209], v176 offset:33792
	ds_read_b128 v[210:213], v176 offset:34816
	ds_read_b128 v[214:217], v176 offset:35840
	ds_read_b128 v[218:221], v176 offset:36864
	ds_read_b128 v[222:225], v176 offset:37888
	ds_read_b128 v[226:229], v176 offset:38912
	ds_read_b128 v[230:233], v176 offset:39936
	global_load_lds_dwordx4 v138, s[46:47]
	s_mov_b32 m0, s56
	s_nop 0
	global_load_lds_dwordx4 v142, s[46:47]
	s_waitcnt vmcnt(8)
	s_waitcnt lgkmcnt(0)
	s_barrier
	s_setprio 1
	v_mfma_f32_16x16x32_bf16 v[126:129], v[160:163], v[202:205], v[126:129]
	v_mfma_f32_16x16x32_bf16 v[126:129], v[164:167], v[206:209], v[126:129]
	v_mfma_f32_16x16x32_bf16 v[122:125], v[178:181], v[202:205], v[122:125]
	v_mfma_f32_16x16x32_bf16 v[122:125], v[182:185], v[206:209], v[122:125]
	v_mfma_f32_16x16x32_bf16 v[106:109], v[178:181], v[210:213], v[106:109]
	v_mfma_f32_16x16x32_bf16 v[106:109], v[182:185], v[214:217], v[106:109]
	v_mfma_f32_16x16x32_bf16 v[110:113], v[160:163], v[210:213], v[110:113]
	v_mfma_f32_16x16x32_bf16 v[110:113], v[164:167], v[214:217], v[110:113]
	v_mfma_f32_16x16x32_bf16 v[94:97], v[160:163], v[218:221], v[94:97]
	v_mfma_f32_16x16x32_bf16 v[94:97], v[164:167], v[222:225], v[94:97]
	v_mfma_f32_16x16x32_bf16 v[90:93], v[178:181], v[218:221], v[90:93]
	v_mfma_f32_16x16x32_bf16 v[90:93], v[182:185], v[222:225], v[90:93]
	v_mfma_f32_16x16x32_bf16 v[74:77], v[178:181], v[226:229], v[74:77]
	v_mfma_f32_16x16x32_bf16 v[74:77], v[182:185], v[230:233], v[74:77]
	v_mfma_f32_16x16x32_bf16 v[78:81], v[160:163], v[226:229], v[78:81]
	v_mfma_f32_16x16x32_bf16 v[78:81], v[164:167], v[230:233], v[78:81]
	v_mfma_f32_16x16x32_bf16 v[118:121], v[186:189], v[202:205], v[118:121]
	v_mfma_f32_16x16x32_bf16 v[118:121], v[190:193], v[206:209], v[118:121]
	v_mfma_f32_16x16x32_bf16 v[114:117], v[194:197], v[202:205], v[114:117]
	v_mfma_f32_16x16x32_bf16 v[114:117], v[198:201], v[206:209], v[114:117]
	v_mfma_f32_16x16x32_bf16 v[98:101], v[194:197], v[210:213], v[98:101]
	v_mfma_f32_16x16x32_bf16 v[98:101], v[198:201], v[214:217], v[98:101]
	v_mfma_f32_16x16x32_bf16 v[102:105], v[186:189], v[210:213], v[102:105]
	v_mfma_f32_16x16x32_bf16 v[102:105], v[190:193], v[214:217], v[102:105]
	v_mfma_f32_16x16x32_bf16 v[86:89], v[186:189], v[218:221], v[86:89]
	v_mfma_f32_16x16x32_bf16 v[86:89], v[190:193], v[222:225], v[86:89]
	v_mfma_f32_16x16x32_bf16 v[82:85], v[194:197], v[218:221], v[82:85]
	v_mfma_f32_16x16x32_bf16 v[82:85], v[198:201], v[222:225], v[82:85]
	s_setprio 2
	s_barrier
	v_mfma_f32_16x16x32_bf16 v[66:69], v[194:197], v[226:229], v[66:69]
	v_mfma_f32_16x16x32_bf16 v[66:69], v[198:201], v[230:233], v[66:69]
	v_mfma_f32_16x16x32_bf16 v[70:73], v[186:189], v[226:229], v[70:73]
	v_mfma_f32_16x16x32_bf16 v[70:73], v[190:193], v[230:233], v[70:73]
	s_setprio 0
	s_nop 0
	s_add_i32 s46, s72, s33
	s_add_u32 s96, s44, 0x80
	s_addc_u32 s97, s45, 0
	s_mov_b32 m0, s46
	ds_read_b128 v[202:205], v176 offset:49152
	ds_read_b128 v[206:209], v176 offset:50176
	ds_read_b128 v[210:213], v176 offset:51200
	ds_read_b128 v[214:217], v176 offset:52224
	ds_read_b128 v[218:221], v176 offset:53248
	ds_read_b128 v[222:225], v176 offset:54272
	ds_read_b128 v[226:229], v176 offset:55296
	ds_read_b128 v[230:233], v176 offset:56320
	global_load_lds_dwordx4 v140, s[96:97]
	s_add_i32 m0, s46, 0x2000
	s_add_u32 s44, s44, 0x40080
	s_addc_u32 s45, s45, 0
	s_add_i32 s46, s73, s33
	global_load_lds_dwordx4 v144, s[96:97]
	s_mov_b32 m0, s46
	s_nop 0
	global_load_lds_dwordx4 v140, s[44:45]
	s_add_i32 m0, s46, 0x2000
	s_nop 0
	global_load_lds_dwordx4 v144, s[44:45]
	s_mov_b32 m0, s57
	s_nop 0
	global_load_lds_dwordx4 v138, s[94:95]
	s_mov_b32 m0, s58
	s_nop 0
	global_load_lds_dwordx4 v142, s[94:95]
	s_waitcnt vmcnt(8)
	s_waitcnt lgkmcnt(0)
	s_barrier
	s_setprio 1
	v_mfma_f32_16x16x32_bf16 v[62:65], v[160:163], v[202:205], v[62:65]
	v_mfma_f32_16x16x32_bf16 v[62:65], v[164:167], v[206:209], v[62:65]
	v_mfma_f32_16x16x32_bf16 v[58:61], v[178:181], v[202:205], v[58:61]
	v_mfma_f32_16x16x32_bf16 v[58:61], v[182:185], v[206:209], v[58:61]
	v_mfma_f32_16x16x32_bf16 v[42:45], v[178:181], v[210:213], v[42:45]
	v_mfma_f32_16x16x32_bf16 v[42:45], v[182:185], v[214:217], v[42:45]
	v_mfma_f32_16x16x32_bf16 v[46:49], v[160:163], v[210:213], v[46:49]
	v_mfma_f32_16x16x32_bf16 v[46:49], v[164:167], v[214:217], v[46:49]
	v_mfma_f32_16x16x32_bf16 v[30:33], v[160:163], v[218:221], v[30:33]
	v_mfma_f32_16x16x32_bf16 v[30:33], v[164:167], v[222:225], v[30:33]
	v_mfma_f32_16x16x32_bf16 v[26:29], v[178:181], v[218:221], v[26:29]
	v_mfma_f32_16x16x32_bf16 v[26:29], v[182:185], v[222:225], v[26:29]
	v_mfma_f32_16x16x32_bf16 v[10:13], v[178:181], v[226:229], v[10:13]
	v_mfma_f32_16x16x32_bf16 v[10:13], v[182:185], v[230:233], v[10:13]
	v_mfma_f32_16x16x32_bf16 v[14:17], v[160:163], v[226:229], v[14:17]
	v_mfma_f32_16x16x32_bf16 v[14:17], v[164:167], v[230:233], v[14:17]
	v_mfma_f32_16x16x32_bf16 v[54:57], v[186:189], v[202:205], v[54:57]
	v_mfma_f32_16x16x32_bf16 v[54:57], v[190:193], v[206:209], v[54:57]
	v_mfma_f32_16x16x32_bf16 v[50:53], v[194:197], v[202:205], v[50:53]
	v_mfma_f32_16x16x32_bf16 v[50:53], v[198:201], v[206:209], v[50:53]
	v_mfma_f32_16x16x32_bf16 v[34:37], v[194:197], v[210:213], v[34:37]
	v_mfma_f32_16x16x32_bf16 v[34:37], v[198:201], v[214:217], v[34:37]
	v_mfma_f32_16x16x32_bf16 v[38:41], v[186:189], v[210:213], v[38:41]
	v_mfma_f32_16x16x32_bf16 v[38:41], v[190:193], v[214:217], v[38:41]
	v_mfma_f32_16x16x32_bf16 v[22:25], v[186:189], v[218:221], v[22:25]
	v_mfma_f32_16x16x32_bf16 v[22:25], v[190:193], v[222:225], v[22:25]
	v_mfma_f32_16x16x32_bf16 v[18:21], v[194:197], v[218:221], v[18:21]
	v_mfma_f32_16x16x32_bf16 v[18:21], v[198:201], v[222:225], v[18:21]
	s_setprio 2
	s_barrier
	v_mfma_f32_16x16x32_bf16 v[2:5], v[194:197], v[226:229], v[2:5]
	v_mfma_f32_16x16x32_bf16 v[2:5], v[198:201], v[230:233], v[2:5]
	v_mfma_f32_16x16x32_bf16 v[6:9], v[186:189], v[226:229], v[6:9]
	v_mfma_f32_16x16x32_bf16 v[6:9], v[190:193], v[230:233], v[6:9]
	s_setprio 0
	s_nop 0
	s_add_i32 s67, s67, 2
	s_add_u32 s30, s30, 0x100
	s_addc_u32 s31, s31, 0
	s_cmp_gt_u32 s67, 13
	s_cbranch_scc1 .LBB0_181

.LBB0_587:
	s_add_u32 s4, s36, s38
	s_addc_u32 s5, s37, s39
	s_add_u32 s4, s4, 0x100
	s_addc_u32 s5, s5, 0
	s_add_u32 s72, s65, s38
	s_addc_u32 s73, s66, s39
	s_add_i32 s74, 0, 0x10000
	v_add_u32_e32 v3, s74, v213
	ds_read_b128 v[134:137], v3
	ds_read_b128 v[138:141], v3 offset:1024
	ds_read_b128 v[142:145], v3 offset:2048
	ds_read_b128 v[146:149], v3 offset:3072
	v_add_u32_e32 v3, s63, v213
	ds_read_b128 v[150:153], v3
	ds_read_b128 v[154:157], v3 offset:1024
	ds_read_b128 v[158:161], v3 offset:2048
	ds_read_b128 v[162:165], v3 offset:3072
	s_cmpk_eq_i32 s38, 0x700
	s_cselect_b32 s41, s3, s5
	s_cselect_b32 s40, s23, s4
	s_cselect_b32 s5, s25, s73
	s_cselect_b32 s4, s64, s72
	v_lshl_add_u64 v[4:5], v[170:171], 0, s[38:39]
	s_add_i32 m0, s31, 0xc000
	ds_read_b128 v[166:169], v217
	ds_read_b128 v[176:179], v217 offset:1024
	ds_read_b128 v[180:183], v217 offset:2048
	ds_read_b128 v[184:187], v217 offset:3072
	ds_read_b128 v[188:191], v217 offset:4096
	ds_read_b128 v[192:195], v217 offset:5120
	ds_read_b128 v[218:221], v217 offset:6144
	ds_read_b128 v[222:225], v217 offset:7168
	global_load_lds_dwordx4 v[4:5], off
	v_lshl_add_u64 v[4:5], v[172:173], 0, s[38:39]
	s_add_i32 m0, s31, 0xe000
	s_nop 0
	global_load_lds_dwordx4 v[4:5], off
	s_waitcnt vmcnt(8)
	s_waitcnt lgkmcnt(0)
	s_barrier
	s_setprio 1
	v_mfma_f32_16x16x32_bf16 v[130:133], v[134:137], v[166:169], v[130:133]
	v_mfma_f32_16x16x32_bf16 v[130:133], v[138:141], v[176:179], v[130:133]
	v_mfma_f32_16x16x32_bf16 v[126:129], v[142:145], v[166:169], v[126:129]
	v_mfma_f32_16x16x32_bf16 v[126:129], v[146:149], v[176:179], v[126:129]
	v_mfma_f32_16x16x32_bf16 v[110:113], v[142:145], v[180:183], v[110:113]
	v_mfma_f32_16x16x32_bf16 v[110:113], v[146:149], v[184:187], v[110:113]
	v_mfma_f32_16x16x32_bf16 v[114:117], v[134:137], v[180:183], v[114:117]
	v_mfma_f32_16x16x32_bf16 v[114:117], v[138:141], v[184:187], v[114:117]
	v_mfma_f32_16x16x32_bf16 v[98:101], v[134:137], v[188:191], v[98:101]
	v_mfma_f32_16x16x32_bf16 v[98:101], v[138:141], v[192:195], v[98:101]
	v_mfma_f32_16x16x32_bf16 v[94:97], v[142:145], v[188:191], v[94:97]
	v_mfma_f32_16x16x32_bf16 v[94:97], v[146:149], v[192:195], v[94:97]
	v_mfma_f32_16x16x32_bf16 v[78:81], v[142:145], v[218:221], v[78:81]
	v_mfma_f32_16x16x32_bf16 v[78:81], v[146:149], v[222:225], v[78:81]
	v_mfma_f32_16x16x32_bf16 v[82:85], v[134:137], v[218:221], v[82:85]
	v_mfma_f32_16x16x32_bf16 v[82:85], v[138:141], v[222:225], v[82:85]
	v_mfma_f32_16x16x32_bf16 v[122:125], v[150:153], v[166:169], v[122:125]
	v_mfma_f32_16x16x32_bf16 v[122:125], v[154:157], v[176:179], v[122:125]
	v_mfma_f32_16x16x32_bf16 v[118:121], v[158:161], v[166:169], v[118:121]
	v_mfma_f32_16x16x32_bf16 v[118:121], v[162:165], v[176:179], v[118:121]
	v_mfma_f32_16x16x32_bf16 v[102:105], v[158:161], v[180:183], v[102:105]
	v_mfma_f32_16x16x32_bf16 v[102:105], v[162:165], v[184:187], v[102:105]
	v_mfma_f32_16x16x32_bf16 v[106:109], v[150:153], v[180:183], v[106:109]
	v_mfma_f32_16x16x32_bf16 v[106:109], v[154:157], v[184:187], v[106:109]
	v_mfma_f32_16x16x32_bf16 v[90:93], v[150:153], v[188:191], v[90:93]
	v_mfma_f32_16x16x32_bf16 v[90:93], v[154:157], v[192:195], v[90:93]
	v_mfma_f32_16x16x32_bf16 v[86:89], v[158:161], v[188:191], v[86:89]
	v_mfma_f32_16x16x32_bf16 v[86:89], v[162:165], v[192:195], v[86:89]
	s_setprio 2
	s_barrier
	v_mfma_f32_16x16x32_bf16 v[70:73], v[158:161], v[218:221], v[70:73]
	v_mfma_f32_16x16x32_bf16 v[70:73], v[162:165], v[222:225], v[70:73]
	v_mfma_f32_16x16x32_bf16 v[74:77], v[150:153], v[218:221], v[74:77]
	v_mfma_f32_16x16x32_bf16 v[74:77], v[154:157], v[222:225], v[74:77]
	s_setprio 0
	s_nop 0
	s_add_i32 s72, s74, s33
	v_lshl_add_u64 v[196:197], s[4:5], 0, v[200:201]
	s_mov_b32 m0, s72
	ds_read_b128 v[166:169], v217 offset:16384
	ds_read_b128 v[176:179], v217 offset:17408
	ds_read_b128 v[180:183], v217 offset:18432
	ds_read_b128 v[184:187], v217 offset:19456
	ds_read_b128 v[188:191], v217 offset:20480
	ds_read_b128 v[192:195], v217 offset:21504
	ds_read_b128 v[218:221], v217 offset:22528
	ds_read_b128 v[222:225], v217 offset:23552
	global_load_lds_dwordx4 v[196:197], off
	s_add_i32 m0, s72, 0x2000
	s_add_u32 s72, s4, 0x40000
	v_lshl_add_u64 v[210:211], s[4:5], 0, v[204:205]
	s_addc_u32 s73, s5, 0
	s_add_i32 s74, s63, s33
	global_load_lds_dwordx4 v[210:211], off
	v_lshl_add_u64 v[4:5], s[72:73], 0, v[200:201]
	s_mov_b32 m0, s74
	v_lshl_add_u64 v[226:227], s[40:41], 0, v[198:199]
	global_load_lds_dwordx4 v[4:5], off
	v_lshl_add_u64 v[4:5], s[72:73], 0, v[204:205]
	s_add_i32 m0, s74, 0x2000
	v_lshl_add_u64 v[230:231], s[40:41], 0, v[202:203]
	global_load_lds_dwordx4 v[4:5], off
	s_mov_b32 m0, s31
	s_nop 0
	global_load_lds_dwordx4 v[226:227], off
	s_mov_b32 m0, s42
	s_nop 0
	global_load_lds_dwordx4 v[230:231], off
	s_waitcnt vmcnt(8)
	s_waitcnt lgkmcnt(0)
	s_barrier
	s_setprio 1
	v_mfma_f32_16x16x32_bf16 v[66:69], v[134:137], v[166:169], v[66:69]
	v_mfma_f32_16x16x32_bf16 v[66:69], v[138:141], v[176:179], v[66:69]
	v_mfma_f32_16x16x32_bf16 v[62:65], v[142:145], v[166:169], v[62:65]
	v_mfma_f32_16x16x32_bf16 v[62:65], v[146:149], v[176:179], v[62:65]
	v_mfma_f32_16x16x32_bf16 v[46:49], v[142:145], v[180:183], v[46:49]
	v_mfma_f32_16x16x32_bf16 v[46:49], v[146:149], v[184:187], v[46:49]
	v_mfma_f32_16x16x32_bf16 v[50:53], v[134:137], v[180:183], v[50:53]
	v_mfma_f32_16x16x32_bf16 v[50:53], v[138:141], v[184:187], v[50:53]
	v_mfma_f32_16x16x32_bf16 v[34:37], v[134:137], v[188:191], v[34:37]
	v_mfma_f32_16x16x32_bf16 v[34:37], v[138:141], v[192:195], v[34:37]
	v_mfma_f32_16x16x32_bf16 v[30:33], v[142:145], v[188:191], v[30:33]
	v_mfma_f32_16x16x32_bf16 v[30:33], v[146:149], v[192:195], v[30:33]
	v_mfma_f32_16x16x32_bf16 v[14:17], v[142:145], v[218:221], v[14:17]
	v_mfma_f32_16x16x32_bf16 v[14:17], v[146:149], v[222:225], v[14:17]
	v_mfma_f32_16x16x32_bf16 v[18:21], v[134:137], v[218:221], v[18:21]
	v_mfma_f32_16x16x32_bf16 v[18:21], v[138:141], v[222:225], v[18:21]
	v_mfma_f32_16x16x32_bf16 v[58:61], v[150:153], v[166:169], v[58:61]
	v_mfma_f32_16x16x32_bf16 v[58:61], v[154:157], v[176:179], v[58:61]
	v_mfma_f32_16x16x32_bf16 v[54:57], v[158:161], v[166:169], v[54:57]
	v_mfma_f32_16x16x32_bf16 v[54:57], v[162:165], v[176:179], v[54:57]
	v_mfma_f32_16x16x32_bf16 v[38:41], v[158:161], v[180:183], v[38:41]
	v_mfma_f32_16x16x32_bf16 v[38:41], v[162:165], v[184:187], v[38:41]
	v_mfma_f32_16x16x32_bf16 v[42:45], v[150:153], v[180:183], v[42:45]
	v_mfma_f32_16x16x32_bf16 v[42:45], v[154:157], v[184:187], v[42:45]
	v_mfma_f32_16x16x32_bf16 v[26:29], v[150:153], v[188:191], v[26:29]
	v_mfma_f32_16x16x32_bf16 v[26:29], v[154:157], v[192:195], v[26:29]
	v_mfma_f32_16x16x32_bf16 v[22:25], v[158:161], v[188:191], v[22:25]
	v_mfma_f32_16x16x32_bf16 v[22:25], v[162:165], v[192:195], v[22:25]
	s_setprio 2
	s_barrier
	v_mfma_f32_16x16x32_bf16 v[4:7], v[158:161], v[218:221], v[6:9]
	v_mfma_f32_16x16x32_bf16 v[4:7], v[162:165], v[222:225], v[4:7]
	v_mfma_f32_16x16x32_bf16 v[10:13], v[150:153], v[218:221], v[10:13]
	v_mfma_f32_16x16x32_bf16 v[10:13], v[154:157], v[222:225], v[10:13]
	s_setprio 0
	s_nop 0
	s_add_i32 s72, 0, 0x18000
	v_add_u32_e32 v3, s72, v213
	s_add_i32 s73, 0, 0x1c000
	ds_read_b128 v[134:137], v3
	ds_read_b128 v[138:141], v3 offset:1024
	ds_read_b128 v[142:145], v3 offset:2048
	ds_read_b128 v[146:149], v3 offset:3072
	v_add_u32_e32 v3, s73, v213
	ds_read_b128 v[150:153], v3
	ds_read_b128 v[154:157], v3 offset:1024
	ds_read_b128 v[158:161], v3 offset:2048
	ds_read_b128 v[162:165], v3 offset:3072
	s_add_u32 s40, s40, 0x40000
	s_addc_u32 s41, s41, 0
	s_mov_b32 m0, s43
	v_lshl_add_u64 v[8:9], s[40:41], 0, v[198:199]
	ds_read_b128 v[166:169], v217 offset:32768
	ds_read_b128 v[176:179], v217 offset:33792
	ds_read_b128 v[180:183], v217 offset:34816
	ds_read_b128 v[184:187], v217 offset:35840
	ds_read_b128 v[188:191], v217 offset:36864
	ds_read_b128 v[192:195], v217 offset:37888
	ds_read_b128 v[218:221], v217 offset:38912
	ds_read_b128 v[222:225], v217 offset:39936
	global_load_lds_dwordx4 v[8:9], off
	v_lshl_add_u64 v[8:9], s[40:41], 0, v[202:203]
	s_mov_b32 m0, s44
	s_nop 0
	global_load_lds_dwordx4 v[8:9], off
	s_waitcnt vmcnt(8)
	s_waitcnt lgkmcnt(0)
	s_barrier
	s_setprio 1
	v_mfma_f32_16x16x32_bf16 v[130:133], v[134:137], v[166:169], v[130:133]
	v_mfma_f32_16x16x32_bf16 v[130:133], v[138:141], v[176:179], v[130:133]
	v_mfma_f32_16x16x32_bf16 v[126:129], v[142:145], v[166:169], v[126:129]
	v_mfma_f32_16x16x32_bf16 v[126:129], v[146:149], v[176:179], v[126:129]
	v_mfma_f32_16x16x32_bf16 v[110:113], v[142:145], v[180:183], v[110:113]
	v_mfma_f32_16x16x32_bf16 v[110:113], v[146:149], v[184:187], v[110:113]
	v_mfma_f32_16x16x32_bf16 v[114:117], v[134:137], v[180:183], v[114:117]
	v_mfma_f32_16x16x32_bf16 v[114:117], v[138:141], v[184:187], v[114:117]
	v_mfma_f32_16x16x32_bf16 v[98:101], v[134:137], v[188:191], v[98:101]
	v_mfma_f32_16x16x32_bf16 v[98:101], v[138:141], v[192:195], v[98:101]
	v_mfma_f32_16x16x32_bf16 v[94:97], v[142:145], v[188:191], v[94:97]
	v_mfma_f32_16x16x32_bf16 v[94:97], v[146:149], v[192:195], v[94:97]
	v_mfma_f32_16x16x32_bf16 v[78:81], v[142:145], v[218:221], v[78:81]
	v_mfma_f32_16x16x32_bf16 v[78:81], v[146:149], v[222:225], v[78:81]
	v_mfma_f32_16x16x32_bf16 v[82:85], v[134:137], v[218:221], v[82:85]
	v_mfma_f32_16x16x32_bf16 v[82:85], v[138:141], v[222:225], v[82:85]
	v_mfma_f32_16x16x32_bf16 v[122:125], v[150:153], v[166:169], v[122:125]
	v_mfma_f32_16x16x32_bf16 v[122:125], v[154:157], v[176:179], v[122:125]
	v_mfma_f32_16x16x32_bf16 v[118:121], v[158:161], v[166:169], v[118:121]
	v_mfma_f32_16x16x32_bf16 v[118:121], v[162:165], v[176:179], v[118:121]
	v_mfma_f32_16x16x32_bf16 v[102:105], v[158:161], v[180:183], v[102:105]
	v_mfma_f32_16x16x32_bf16 v[102:105], v[162:165], v[184:187], v[102:105]
	v_mfma_f32_16x16x32_bf16 v[106:109], v[150:153], v[180:183], v[106:109]
	v_mfma_f32_16x16x32_bf16 v[106:109], v[154:157], v[184:187], v[106:109]
	v_mfma_f32_16x16x32_bf16 v[90:93], v[150:153], v[188:191], v[90:93]
	v_mfma_f32_16x16x32_bf16 v[90:93], v[154:157], v[192:195], v[90:93]
	v_mfma_f32_16x16x32_bf16 v[86:89], v[158:161], v[188:191], v[86:89]
	v_mfma_f32_16x16x32_bf16 v[86:89], v[162:165], v[192:195], v[86:89]
	s_setprio 2
	s_barrier
	v_mfma_f32_16x16x32_bf16 v[70:73], v[158:161], v[218:221], v[70:73]
	v_mfma_f32_16x16x32_bf16 v[70:73], v[162:165], v[222:225], v[70:73]
	v_mfma_f32_16x16x32_bf16 v[74:77], v[150:153], v[218:221], v[74:77]
	v_mfma_f32_16x16x32_bf16 v[74:77], v[154:157], v[222:225], v[74:77]
	s_setprio 0
	s_nop 0
	s_add_i32 s40, s72, s33
	v_lshl_add_u64 v[8:9], v[196:197], 0, s[10:11]
	s_mov_b32 m0, s40
	ds_read_b128 v[166:169], v217 offset:49152
	ds_read_b128 v[176:179], v217 offset:50176
	ds_read_b128 v[180:183], v217 offset:51200
	ds_read_b128 v[184:187], v217 offset:52224
	ds_read_b128 v[188:191], v217 offset:53248
	ds_read_b128 v[192:195], v217 offset:54272
	ds_read_b128 v[218:221], v217 offset:55296
	ds_read_b128 v[222:225], v217 offset:56320
	global_load_lds_dwordx4 v[8:9], off
	s_add_i32 m0, s40, 0x2000
	s_add_u32 s4, s4, 0x40080
	v_lshl_add_u64 v[8:9], v[210:211], 0, s[10:11]
	s_addc_u32 s5, s5, 0
	s_add_i32 s40, s73, s33
	global_load_lds_dwordx4 v[8:9], off
	v_lshl_add_u64 v[8:9], s[4:5], 0, v[200:201]
	s_mov_b32 m0, s40
	s_nop 0
	global_load_lds_dwordx4 v[8:9], off
	v_lshl_add_u64 v[8:9], s[4:5], 0, v[204:205]
	s_add_i32 m0, s40, 0x2000
	s_nop 0
	global_load_lds_dwordx4 v[8:9], off
	v_lshl_add_u64 v[8:9], v[226:227], 0, s[10:11]
	s_mov_b32 m0, s47
	s_nop 0
	global_load_lds_dwordx4 v[8:9], off
	v_lshl_add_u64 v[8:9], v[230:231], 0, s[10:11]
	s_mov_b32 m0, s48
	s_nop 0
	global_load_lds_dwordx4 v[8:9], off
	s_waitcnt vmcnt(8)
	s_waitcnt lgkmcnt(0)
	s_barrier
	s_setprio 1
	v_mfma_f32_16x16x32_bf16 v[66:69], v[134:137], v[166:169], v[66:69]
	v_mfma_f32_16x16x32_bf16 v[66:69], v[138:141], v[176:179], v[66:69]
	v_mfma_f32_16x16x32_bf16 v[62:65], v[142:145], v[166:169], v[62:65]
	v_mfma_f32_16x16x32_bf16 v[62:65], v[146:149], v[176:179], v[62:65]
	v_mfma_f32_16x16x32_bf16 v[46:49], v[142:145], v[180:183], v[46:49]
	v_mfma_f32_16x16x32_bf16 v[46:49], v[146:149], v[184:187], v[46:49]
	v_mfma_f32_16x16x32_bf16 v[50:53], v[134:137], v[180:183], v[50:53]
	v_mfma_f32_16x16x32_bf16 v[50:53], v[138:141], v[184:187], v[50:53]
	v_mfma_f32_16x16x32_bf16 v[34:37], v[134:137], v[188:191], v[34:37]
	v_mfma_f32_16x16x32_bf16 v[34:37], v[138:141], v[192:195], v[34:37]
	v_mfma_f32_16x16x32_bf16 v[30:33], v[142:145], v[188:191], v[30:33]
	v_mfma_f32_16x16x32_bf16 v[30:33], v[146:149], v[192:195], v[30:33]
	v_mfma_f32_16x16x32_bf16 v[14:17], v[142:145], v[218:221], v[14:17]
	v_mfma_f32_16x16x32_bf16 v[14:17], v[146:149], v[222:225], v[14:17]
	v_mfma_f32_16x16x32_bf16 v[18:21], v[134:137], v[218:221], v[18:21]
	v_mfma_f32_16x16x32_bf16 v[18:21], v[138:141], v[222:225], v[18:21]
	v_mfma_f32_16x16x32_bf16 v[58:61], v[150:153], v[166:169], v[58:61]
	v_mfma_f32_16x16x32_bf16 v[58:61], v[154:157], v[176:179], v[58:61]
	v_mfma_f32_16x16x32_bf16 v[54:57], v[158:161], v[166:169], v[54:57]
	v_mfma_f32_16x16x32_bf16 v[54:57], v[162:165], v[176:179], v[54:57]
	v_mfma_f32_16x16x32_bf16 v[42:45], v[150:153], v[180:183], v[42:45]
	v_mfma_f32_16x16x32_bf16 v[42:45], v[154:157], v[184:187], v[42:45]
	v_mfma_f32_16x16x32_bf16 v[38:41], v[158:161], v[180:183], v[38:41]
	v_mfma_f32_16x16x32_bf16 v[38:41], v[162:165], v[184:187], v[38:41]
	v_mfma_f32_16x16x32_bf16 v[26:29], v[150:153], v[188:191], v[26:29]
	v_mfma_f32_16x16x32_bf16 v[26:29], v[154:157], v[192:195], v[26:29]
	v_mfma_f32_16x16x32_bf16 v[22:25], v[158:161], v[188:191], v[22:25]
	v_mfma_f32_16x16x32_bf16 v[22:25], v[162:165], v[192:195], v[22:25]
	s_setprio 2
	s_barrier
	v_mfma_f32_16x16x32_bf16 v[8:11], v[150:153], v[218:221], v[10:13]
	v_mfma_f32_16x16x32_bf16 v[10:13], v[154:157], v[222:225], v[8:11]
	v_mfma_f32_16x16x32_bf16 v[4:7], v[158:161], v[218:221], v[4:7]
	v_mfma_f32_16x16x32_bf16 v[6:9], v[162:165], v[222:225], v[4:7]
	s_setprio 0
	s_nop 0
	s_add_i32 s67, s67, 2
	s_add_u32 s38, s38, 0x100
	s_addc_u32 s39, s39, 0
	s_cmp_gt_u32 s67, 13
	s_cbranch_scc1 .LBB0_590

.LBB0_760:
	ds_read_b128 v[114:117], v232
	ds_read_b128 v[118:121], v232 offset:1024
	ds_read_b128 v[130:133], v232 offset:2048
	ds_read_b128 v[138:141], v232 offset:3072
	ds_read_b128 v[146:149], v233
	ds_read_b128 v[150:153], v233 offset:1024
	ds_read_b128 v[154:157], v233 offset:2048
	ds_read_b128 v[158:161], v233 offset:3072
	s_add_u32 s30, s28, 0xfffc0080
	s_addc_u32 s31, s29, -1
	s_cmp_eq_u32 s47, 12
	s_cselect_b32 s35, s3, s31
	s_cselect_b32 s34, s17, s30
	s_cselect_b32 s31, s19, s46
	s_cselect_b32 s30, s27, s45
	v_lshl_add_u64 v[206:207], s[28:29], 0, v[202:203]
	s_add_i32 m0, s36, 0xc000
	ds_read_b128 v[162:165], v234
	ds_read_b128 v[166:169], v234 offset:1024
	ds_read_b128 v[170:173], v234 offset:2048
	ds_read_b128 v[174:177], v234 offset:3072
	ds_read_b128 v[178:181], v234 offset:4096
	ds_read_b128 v[182:185], v234 offset:5120
	ds_read_b128 v[186:189], v234 offset:6144
	ds_read_b128 v[190:193], v234 offset:7168
	global_load_lds_dwordx4 v[206:207], off
	v_lshl_add_u64 v[206:207], s[28:29], 0, v[204:205]
	s_add_i32 m0, s36, 0xe000
	s_nop 0
	global_load_lds_dwordx4 v[206:207], off
	s_waitcnt vmcnt(8)
	s_waitcnt lgkmcnt(0)
	s_barrier
	s_setprio 1
	v_mfma_f32_16x16x32_bf16 v[142:145], v[114:117], v[162:165], v[142:145]
	v_mfma_f32_16x16x32_bf16 v[142:145], v[118:121], v[166:169], v[142:145]
	v_mfma_f32_16x16x32_bf16 v[134:137], v[130:133], v[162:165], v[134:137]
	v_mfma_f32_16x16x32_bf16 v[134:137], v[138:141], v[166:169], v[134:137]
	v_mfma_f32_16x16x32_bf16 v[106:109], v[130:133], v[170:173], v[106:109]
	v_mfma_f32_16x16x32_bf16 v[106:109], v[138:141], v[174:177], v[106:109]
	v_mfma_f32_16x16x32_bf16 v[110:113], v[114:117], v[170:173], v[110:113]
	v_mfma_f32_16x16x32_bf16 v[110:113], v[118:121], v[174:177], v[110:113]
	v_mfma_f32_16x16x32_bf16 v[94:97], v[114:117], v[178:181], v[94:97]
	v_mfma_f32_16x16x32_bf16 v[94:97], v[118:121], v[182:185], v[94:97]
	v_mfma_f32_16x16x32_bf16 v[90:93], v[130:133], v[178:181], v[90:93]
	v_mfma_f32_16x16x32_bf16 v[90:93], v[138:141], v[182:185], v[90:93]
	v_mfma_f32_16x16x32_bf16 v[74:77], v[130:133], v[186:189], v[74:77]
	v_mfma_f32_16x16x32_bf16 v[74:77], v[138:141], v[190:193], v[74:77]
	v_mfma_f32_16x16x32_bf16 v[78:81], v[114:117], v[186:189], v[78:81]
	v_mfma_f32_16x16x32_bf16 v[78:81], v[118:121], v[190:193], v[78:81]
	v_mfma_f32_16x16x32_bf16 v[126:129], v[146:149], v[162:165], v[126:129]
	v_mfma_f32_16x16x32_bf16 v[126:129], v[150:153], v[166:169], v[126:129]
	v_mfma_f32_16x16x32_bf16 v[122:125], v[154:157], v[162:165], v[122:125]
	v_mfma_f32_16x16x32_bf16 v[122:125], v[158:161], v[166:169], v[122:125]
	v_mfma_f32_16x16x32_bf16 v[98:101], v[154:157], v[170:173], v[98:101]
	v_mfma_f32_16x16x32_bf16 v[98:101], v[158:161], v[174:177], v[98:101]
	v_mfma_f32_16x16x32_bf16 v[102:105], v[146:149], v[170:173], v[102:105]
	v_mfma_f32_16x16x32_bf16 v[102:105], v[150:153], v[174:177], v[102:105]
	v_mfma_f32_16x16x32_bf16 v[86:89], v[146:149], v[178:181], v[86:89]
	v_mfma_f32_16x16x32_bf16 v[86:89], v[150:153], v[182:185], v[86:89]
	v_mfma_f32_16x16x32_bf16 v[82:85], v[154:157], v[178:181], v[82:85]
	v_mfma_f32_16x16x32_bf16 v[82:85], v[158:161], v[182:185], v[82:85]
	s_setprio 2
	s_barrier
	v_mfma_f32_16x16x32_bf16 v[66:69], v[154:157], v[186:189], v[66:69]
	v_mfma_f32_16x16x32_bf16 v[66:69], v[158:161], v[190:193], v[66:69]
	v_mfma_f32_16x16x32_bf16 v[70:73], v[146:149], v[186:189], v[70:73]
	v_mfma_f32_16x16x32_bf16 v[70:73], v[150:153], v[190:193], v[70:73]
	s_setprio 0
	s_nop 0
	s_add_i32 s48, s43, s33
	v_lshl_add_u64 v[206:207], s[30:31], 0, v[196:197]
	s_mov_b32 m0, s48
	ds_read_b128 v[162:165], v234 offset:16384
	ds_read_b128 v[166:169], v234 offset:17408
	ds_read_b128 v[170:173], v234 offset:18432
	ds_read_b128 v[174:177], v234 offset:19456
	ds_read_b128 v[178:181], v234 offset:20480
	ds_read_b128 v[182:185], v234 offset:21504
	ds_read_b128 v[186:189], v234 offset:22528
	ds_read_b128 v[190:193], v234 offset:23552
	global_load_lds_dwordx4 v[206:207], off
	s_add_i32 m0, s48, 0x2000
	s_add_u32 s48, s30, 0x40000
	v_lshl_add_u64 v[208:209], s[30:31], 0, v[200:201]
	s_addc_u32 s49, s31, 0
	s_add_i32 s50, s44, s33
	global_load_lds_dwordx4 v[208:209], off
	v_lshl_add_u64 v[210:211], s[48:49], 0, v[196:197]
	s_mov_b32 m0, s50
	v_lshl_add_u64 v[212:213], s[34:35], 0, v[198:199]
	global_load_lds_dwordx4 v[210:211], off
	v_lshl_add_u64 v[210:211], s[48:49], 0, v[200:201]
	s_add_i32 m0, s50, 0x2000
	s_nop 0
	global_load_lds_dwordx4 v[210:211], off
	v_lshl_add_u64 v[210:211], s[34:35], 0, v[194:195]
	s_mov_b32 m0, s36
	s_nop 0
	global_load_lds_dwordx4 v[210:211], off
	s_mov_b32 m0, s37
	s_nop 0
	global_load_lds_dwordx4 v[212:213], off
	s_waitcnt vmcnt(8)
	s_waitcnt lgkmcnt(0)
	s_barrier
	s_setprio 1
	v_mfma_f32_16x16x32_bf16 v[62:65], v[114:117], v[162:165], v[62:65]
	v_mfma_f32_16x16x32_bf16 v[62:65], v[118:121], v[166:169], v[62:65]
	v_mfma_f32_16x16x32_bf16 v[58:61], v[130:133], v[162:165], v[58:61]
	v_mfma_f32_16x16x32_bf16 v[58:61], v[138:141], v[166:169], v[58:61]
	v_mfma_f32_16x16x32_bf16 v[42:45], v[130:133], v[170:173], v[42:45]
	v_mfma_f32_16x16x32_bf16 v[42:45], v[138:141], v[174:177], v[42:45]
	v_mfma_f32_16x16x32_bf16 v[46:49], v[114:117], v[170:173], v[46:49]
	v_mfma_f32_16x16x32_bf16 v[46:49], v[118:121], v[174:177], v[46:49]
	v_mfma_f32_16x16x32_bf16 v[30:33], v[114:117], v[178:181], v[30:33]
	v_mfma_f32_16x16x32_bf16 v[30:33], v[118:121], v[182:185], v[30:33]
	v_mfma_f32_16x16x32_bf16 v[26:29], v[130:133], v[178:181], v[26:29]
	v_mfma_f32_16x16x32_bf16 v[26:29], v[138:141], v[182:185], v[26:29]
	v_mfma_f32_16x16x32_bf16 v[10:13], v[130:133], v[186:189], v[10:13]
	v_mfma_f32_16x16x32_bf16 v[10:13], v[138:141], v[190:193], v[10:13]
	v_mfma_f32_16x16x32_bf16 v[14:17], v[114:117], v[186:189], v[14:17]
	v_mfma_f32_16x16x32_bf16 v[14:17], v[118:121], v[190:193], v[14:17]
	v_mfma_f32_16x16x32_bf16 v[54:57], v[146:149], v[162:165], v[54:57]
	v_mfma_f32_16x16x32_bf16 v[54:57], v[150:153], v[166:169], v[54:57]
	v_mfma_f32_16x16x32_bf16 v[50:53], v[154:157], v[162:165], v[50:53]
	v_mfma_f32_16x16x32_bf16 v[50:53], v[158:161], v[166:169], v[50:53]
	v_mfma_f32_16x16x32_bf16 v[34:37], v[154:157], v[170:173], v[34:37]
	v_mfma_f32_16x16x32_bf16 v[34:37], v[158:161], v[174:177], v[34:37]
	v_mfma_f32_16x16x32_bf16 v[38:41], v[146:149], v[170:173], v[38:41]
	v_mfma_f32_16x16x32_bf16 v[38:41], v[150:153], v[174:177], v[38:41]
	v_mfma_f32_16x16x32_bf16 v[22:25], v[146:149], v[178:181], v[22:25]
	v_mfma_f32_16x16x32_bf16 v[22:25], v[150:153], v[182:185], v[22:25]
	v_mfma_f32_16x16x32_bf16 v[18:21], v[154:157], v[178:181], v[18:21]
	v_mfma_f32_16x16x32_bf16 v[18:21], v[158:161], v[182:185], v[18:21]
	s_setprio 2
	s_barrier
	v_mfma_f32_16x16x32_bf16 v[2:5], v[154:157], v[186:189], v[2:5]
	v_mfma_f32_16x16x32_bf16 v[2:5], v[158:161], v[190:193], v[2:5]
	v_mfma_f32_16x16x32_bf16 v[6:9], v[146:149], v[186:189], v[6:9]
	v_mfma_f32_16x16x32_bf16 v[6:9], v[150:153], v[190:193], v[6:9]
	s_setprio 0
	s_nop 0
	s_add_i32 s48, 0, 0x18000
	s_add_i32 s49, 0, 0x1c000
	v_add_u32_e32 v138, s48, v230
	v_add_u32_e32 v158, s49, v230
	ds_read_b128 v[114:117], v138
	ds_read_b128 v[118:121], v138 offset:1024
	ds_read_b128 v[130:133], v138 offset:2048
	ds_read_b128 v[138:141], v138 offset:3072
	ds_read_b128 v[146:149], v158
	ds_read_b128 v[150:153], v158 offset:1024
	ds_read_b128 v[154:157], v158 offset:2048
	ds_read_b128 v[158:161], v158 offset:3072
	s_add_u32 s34, s34, 0x40000
	s_addc_u32 s35, s35, 0
	s_mov_b32 m0, s38
	v_lshl_add_u64 v[214:215], s[34:35], 0, v[194:195]
	ds_read_b128 v[162:165], v234 offset:32768
	ds_read_b128 v[166:169], v234 offset:33792
	ds_read_b128 v[170:173], v234 offset:34816
	ds_read_b128 v[174:177], v234 offset:35840
	ds_read_b128 v[178:181], v234 offset:36864
	ds_read_b128 v[182:185], v234 offset:37888
	ds_read_b128 v[186:189], v234 offset:38912
	ds_read_b128 v[190:193], v234 offset:39936
	global_load_lds_dwordx4 v[214:215], off
	v_lshl_add_u64 v[214:215], s[34:35], 0, v[198:199]
	s_mov_b32 m0, s39
	s_nop 0
	global_load_lds_dwordx4 v[214:215], off
	s_waitcnt vmcnt(8)
	s_waitcnt lgkmcnt(0)
	s_barrier
	s_setprio 1
	v_mfma_f32_16x16x32_bf16 v[142:145], v[114:117], v[162:165], v[142:145]
	v_mfma_f32_16x16x32_bf16 v[142:145], v[118:121], v[166:169], v[142:145]
	v_mfma_f32_16x16x32_bf16 v[134:137], v[130:133], v[162:165], v[134:137]
	v_mfma_f32_16x16x32_bf16 v[134:137], v[138:141], v[166:169], v[134:137]
	v_mfma_f32_16x16x32_bf16 v[106:109], v[130:133], v[170:173], v[106:109]
	v_mfma_f32_16x16x32_bf16 v[106:109], v[138:141], v[174:177], v[106:109]
	v_mfma_f32_16x16x32_bf16 v[110:113], v[114:117], v[170:173], v[110:113]
	v_mfma_f32_16x16x32_bf16 v[110:113], v[118:121], v[174:177], v[110:113]
	v_mfma_f32_16x16x32_bf16 v[94:97], v[114:117], v[178:181], v[94:97]
	v_mfma_f32_16x16x32_bf16 v[94:97], v[118:121], v[182:185], v[94:97]
	v_mfma_f32_16x16x32_bf16 v[90:93], v[130:133], v[178:181], v[90:93]
	v_mfma_f32_16x16x32_bf16 v[90:93], v[138:141], v[182:185], v[90:93]
	v_mfma_f32_16x16x32_bf16 v[74:77], v[130:133], v[186:189], v[74:77]
	v_mfma_f32_16x16x32_bf16 v[74:77], v[138:141], v[190:193], v[74:77]
	v_mfma_f32_16x16x32_bf16 v[78:81], v[114:117], v[186:189], v[78:81]
	v_mfma_f32_16x16x32_bf16 v[78:81], v[118:121], v[190:193], v[78:81]
	v_mfma_f32_16x16x32_bf16 v[126:129], v[146:149], v[162:165], v[126:129]
	v_mfma_f32_16x16x32_bf16 v[126:129], v[150:153], v[166:169], v[126:129]
	v_mfma_f32_16x16x32_bf16 v[122:125], v[154:157], v[162:165], v[122:125]
	v_mfma_f32_16x16x32_bf16 v[122:125], v[158:161], v[166:169], v[122:125]
	v_mfma_f32_16x16x32_bf16 v[98:101], v[154:157], v[170:173], v[98:101]
	v_mfma_f32_16x16x32_bf16 v[98:101], v[158:161], v[174:177], v[98:101]
	v_mfma_f32_16x16x32_bf16 v[102:105], v[146:149], v[170:173], v[102:105]
	v_mfma_f32_16x16x32_bf16 v[102:105], v[150:153], v[174:177], v[102:105]
	v_mfma_f32_16x16x32_bf16 v[86:89], v[146:149], v[178:181], v[86:89]
	v_mfma_f32_16x16x32_bf16 v[86:89], v[150:153], v[182:185], v[86:89]
	v_mfma_f32_16x16x32_bf16 v[82:85], v[154:157], v[178:181], v[82:85]
	v_mfma_f32_16x16x32_bf16 v[82:85], v[158:161], v[182:185], v[82:85]
	s_setprio 2
	s_barrier
	v_mfma_f32_16x16x32_bf16 v[66:69], v[154:157], v[186:189], v[66:69]
	v_mfma_f32_16x16x32_bf16 v[66:69], v[158:161], v[190:193], v[66:69]
	v_mfma_f32_16x16x32_bf16 v[70:73], v[146:149], v[186:189], v[70:73]
	v_mfma_f32_16x16x32_bf16 v[70:73], v[150:153], v[190:193], v[70:73]
	s_setprio 0
	s_nop 0
	s_add_i32 s34, s48, s33
	v_lshl_add_u64 v[206:207], v[206:207], 0, s[8:9]
	s_mov_b32 m0, s34
	ds_read_b128 v[162:165], v234 offset:49152
	ds_read_b128 v[166:169], v234 offset:50176
	ds_read_b128 v[170:173], v234 offset:51200
	ds_read_b128 v[174:177], v234 offset:52224
	ds_read_b128 v[178:181], v234 offset:53248
	ds_read_b128 v[182:185], v234 offset:54272
	ds_read_b128 v[186:189], v234 offset:55296
	ds_read_b128 v[190:193], v234 offset:56320
	global_load_lds_dwordx4 v[206:207], off
	s_add_i32 m0, s34, 0x2000
	s_add_u32 s30, s30, 0x40080
	v_lshl_add_u64 v[206:207], v[208:209], 0, s[8:9]
	s_addc_u32 s31, s31, 0
	s_add_i32 s34, s49, s33
	global_load_lds_dwordx4 v[206:207], off
	v_lshl_add_u64 v[206:207], s[30:31], 0, v[196:197]
	s_mov_b32 m0, s34
	s_nop 0
	global_load_lds_dwordx4 v[206:207], off
	v_lshl_add_u64 v[206:207], s[30:31], 0, v[200:201]
	s_add_i32 m0, s34, 0x2000
	s_nop 0
	global_load_lds_dwordx4 v[206:207], off
	v_lshl_add_u64 v[206:207], v[210:211], 0, s[8:9]
	s_mov_b32 m0, s40
	s_nop 0
	global_load_lds_dwordx4 v[206:207], off
	v_lshl_add_u64 v[206:207], v[212:213], 0, s[8:9]
	s_mov_b32 m0, s41
	s_nop 0
	global_load_lds_dwordx4 v[206:207], off
	s_waitcnt vmcnt(8)
	s_waitcnt lgkmcnt(0)
	s_barrier
	s_setprio 1
	v_mfma_f32_16x16x32_bf16 v[62:65], v[114:117], v[162:165], v[62:65]
	v_mfma_f32_16x16x32_bf16 v[62:65], v[118:121], v[166:169], v[62:65]
	v_mfma_f32_16x16x32_bf16 v[58:61], v[130:133], v[162:165], v[58:61]
	v_mfma_f32_16x16x32_bf16 v[58:61], v[138:141], v[166:169], v[58:61]
	v_mfma_f32_16x16x32_bf16 v[42:45], v[130:133], v[170:173], v[42:45]
	v_mfma_f32_16x16x32_bf16 v[42:45], v[138:141], v[174:177], v[42:45]
	v_mfma_f32_16x16x32_bf16 v[46:49], v[114:117], v[170:173], v[46:49]
	v_mfma_f32_16x16x32_bf16 v[46:49], v[118:121], v[174:177], v[46:49]
	v_mfma_f32_16x16x32_bf16 v[30:33], v[114:117], v[178:181], v[30:33]
	v_mfma_f32_16x16x32_bf16 v[30:33], v[118:121], v[182:185], v[30:33]
	v_mfma_f32_16x16x32_bf16 v[26:29], v[130:133], v[178:181], v[26:29]
	v_mfma_f32_16x16x32_bf16 v[26:29], v[138:141], v[182:185], v[26:29]
	v_mfma_f32_16x16x32_bf16 v[10:13], v[130:133], v[186:189], v[10:13]
	v_mfma_f32_16x16x32_bf16 v[10:13], v[138:141], v[190:193], v[10:13]
	v_mfma_f32_16x16x32_bf16 v[14:17], v[114:117], v[186:189], v[14:17]
	v_mfma_f32_16x16x32_bf16 v[14:17], v[118:121], v[190:193], v[14:17]
	v_mfma_f32_16x16x32_bf16 v[54:57], v[146:149], v[162:165], v[54:57]
	v_mfma_f32_16x16x32_bf16 v[54:57], v[150:153], v[166:169], v[54:57]
	v_mfma_f32_16x16x32_bf16 v[50:53], v[154:157], v[162:165], v[50:53]
	v_mfma_f32_16x16x32_bf16 v[50:53], v[158:161], v[166:169], v[50:53]
	v_mfma_f32_16x16x32_bf16 v[34:37], v[154:157], v[170:173], v[34:37]
	v_mfma_f32_16x16x32_bf16 v[34:37], v[158:161], v[174:177], v[34:37]
	v_mfma_f32_16x16x32_bf16 v[38:41], v[146:149], v[170:173], v[38:41]
	v_mfma_f32_16x16x32_bf16 v[38:41], v[150:153], v[174:177], v[38:41]
	v_mfma_f32_16x16x32_bf16 v[22:25], v[146:149], v[178:181], v[22:25]
	v_mfma_f32_16x16x32_bf16 v[22:25], v[150:153], v[182:185], v[22:25]
	v_mfma_f32_16x16x32_bf16 v[18:21], v[154:157], v[178:181], v[18:21]
	v_mfma_f32_16x16x32_bf16 v[18:21], v[158:161], v[182:185], v[18:21]
	s_setprio 2
	s_barrier
	v_mfma_f32_16x16x32_bf16 v[2:5], v[154:157], v[186:189], v[2:5]
	v_mfma_f32_16x16x32_bf16 v[2:5], v[158:161], v[190:193], v[2:5]
	v_mfma_f32_16x16x32_bf16 v[6:9], v[146:149], v[186:189], v[6:9]
	v_mfma_f32_16x16x32_bf16 v[6:9], v[150:153], v[190:193], v[6:9]
	s_setprio 0
	s_nop 0
	s_add_i32 s47, s47, 2
	s_add_u32 s28, s28, 0x100
	s_addc_u32 s29, s29, 0
	s_add_u32 s45, s45, 0x100
	s_addc_u32 s46, s46, 0
	s_cmp_gt_u32 s47, 13
	s_cbranch_scc0 .LBB0_760
	s_and_b64 vcc, exec, s[10:11]
	s_cbranch_vccz .LBB0_763
	s_barrier

.LBB0_944:
	s_ashr_i32 s9, s8, 31
	s_lshl_b64 s[14:15], s[8:9], 19
	s_add_u32 s14, s64, s14
	s_addc_u32 s15, s65, s15
	s_and_b64 s[16:17], s[12:13], exec
	s_cselect_b32 s9, s15, s19
	s_cselect_b32 s39, s14, s18
	s_ashr_i32 s11, s10, 31
	s_lshl_b64 s[16:17], s[10:11], 19
	v_readlane_b32 s24, v245, 3
	v_readlane_b32 s25, v245, 4
	s_add_u32 s16, s24, s16
	s_addc_u32 s17, s25, s17
	s_and_b64 s[24:25], s[12:13], exec
	s_cselect_b32 s40, s17, s23
	s_cselect_b32 s41, s16, s22
	s_lshl_b32 s11, s20, 8
	s_add_u32 s42, s22, 0x100
	v_mov_b32_e32 v2, 0
	v_or_b32_e32 v146, s11, v228
	v_lshl_add_u64 v[142:143], s[18:19], 0, v[138:139]
	v_lshl_add_u64 v[144:145], s[18:19], 0, v[140:141]
	s_addc_u32 s43, s23, 0
	s_mov_b32 s44, -2
	s_mov_b64 s[20:21], 0
	ds_read_b128 v[154:157], v229
	ds_read_b128 v[158:161], v229 offset:1024
	ds_read_b128 v[162:165], v229 offset:2048
	ds_read_b128 v[166:169], v229 offset:3072
	s_add_u32 s22, s18, s20
	ds_read_b128 v[170:173], v229 offset:16384
	ds_read_b128 v[174:177], v229 offset:17408
	ds_read_b128 v[178:181], v229 offset:18432
	ds_read_b128 v[182:185], v229 offset:19456
	s_addc_u32 s23, s19, s21
	s_add_u32 s22, s22, 0x100
	s_addc_u32 s23, s23, 0
	s_add_u32 s45, s42, s20
	s_addc_u32 s46, s43, s21
	s_cmpk_eq_i32 s20, 0x700
	s_cselect_b32 s25, s9, s23
	s_cselect_b32 s24, s39, s22
	s_cselect_b32 s23, s40, s46
	s_cselect_b32 s22, s41, s45
	s_add_u32 s48, s18, s20
	s_addc_u32 s49, s19, s21
	s_add_i32 m0, s27, 0xc000
	ds_read_b128 v[186:189], v152
	ds_read_b128 v[190:193], v152 offset:1024
	ds_read_b128 v[194:197], v152 offset:2048
	ds_read_b128 v[198:201], v152 offset:3072
	ds_read_b128 v[202:205], v152 offset:4096
	ds_read_b128 v[206:209], v152 offset:5120
	ds_read_b128 v[210:213], v152 offset:6144
	ds_read_b128 v[214:217], v152 offset:7168
	global_load_lds_dwordx4 v138, s[48:49]
	s_add_i32 m0, s27, 0xe000
	s_nop 0
	global_load_lds_dwordx4 v140, s[48:49]
	s_waitcnt vmcnt(8)
	s_waitcnt lgkmcnt(0)
	s_barrier
	s_setprio 1
	v_mfma_f32_16x16x32_bf16 v[126:129], v[154:157], v[186:189], 0
	v_mfma_f32_16x16x32_bf16 v[126:129], v[158:161], v[190:193], v[126:129]
	v_mfma_f32_16x16x32_bf16 v[118:121], v[162:165], v[186:189], 0
	v_mfma_f32_16x16x32_bf16 v[118:121], v[166:169], v[190:193], v[118:121]
	v_mfma_f32_16x16x32_bf16 v[102:105], v[162:165], v[194:197], 0
	v_mfma_f32_16x16x32_bf16 v[102:105], v[166:169], v[198:201], v[102:105]
	v_mfma_f32_16x16x32_bf16 v[110:113], v[154:157], v[194:197], 0
	v_mfma_f32_16x16x32_bf16 v[110:113], v[158:161], v[198:201], v[110:113]
	v_mfma_f32_16x16x32_bf16 v[94:97], v[154:157], v[202:205], 0
	v_mfma_f32_16x16x32_bf16 v[94:97], v[158:161], v[206:209], v[94:97]
	v_mfma_f32_16x16x32_bf16 v[86:89], v[162:165], v[202:205], 0
	v_mfma_f32_16x16x32_bf16 v[86:89], v[166:169], v[206:209], v[86:89]
	v_mfma_f32_16x16x32_bf16 v[70:73], v[162:165], v[210:213], 0
	v_mfma_f32_16x16x32_bf16 v[70:73], v[166:169], v[214:217], v[70:73]
	v_mfma_f32_16x16x32_bf16 v[78:81], v[154:157], v[210:213], 0
	v_mfma_f32_16x16x32_bf16 v[78:81], v[158:161], v[214:217], v[78:81]
	v_mfma_f32_16x16x32_bf16 v[122:125], v[170:173], v[186:189], 0
	v_mfma_f32_16x16x32_bf16 v[122:125], v[174:177], v[190:193], v[122:125]
	v_mfma_f32_16x16x32_bf16 v[114:117], v[178:181], v[186:189], 0
	v_mfma_f32_16x16x32_bf16 v[114:117], v[182:185], v[190:193], v[114:117]
	v_mfma_f32_16x16x32_bf16 v[98:101], v[178:181], v[194:197], 0
	v_mfma_f32_16x16x32_bf16 v[98:101], v[182:185], v[198:201], v[98:101]
	v_mfma_f32_16x16x32_bf16 v[106:109], v[170:173], v[194:197], 0
	v_mfma_f32_16x16x32_bf16 v[106:109], v[174:177], v[198:201], v[106:109]
	v_mfma_f32_16x16x32_bf16 v[90:93], v[170:173], v[202:205], 0
	v_mfma_f32_16x16x32_bf16 v[90:93], v[174:177], v[206:209], v[90:93]
	v_mfma_f32_16x16x32_bf16 v[82:85], v[178:181], v[202:205], 0
	v_mfma_f32_16x16x32_bf16 v[82:85], v[182:185], v[206:209], v[82:85]
	s_setprio 2
	s_barrier
	v_mfma_f32_16x16x32_bf16 v[66:69], v[178:181], v[210:213], 0
	v_mfma_f32_16x16x32_bf16 v[66:69], v[182:185], v[214:217], v[66:69]
	v_mfma_f32_16x16x32_bf16 v[74:77], v[170:173], v[210:213], 0
	v_mfma_f32_16x16x32_bf16 v[74:77], v[174:177], v[214:217], v[74:77]
	s_setprio 0
	s_nop 0
	s_add_i32 s45, s35, s26
	s_add_u32 s50, s22, 0x80
	s_addc_u32 s51, s23, 0
	s_add_u32 s52, s24, 0x80
	s_addc_u32 s53, s25, 0
	s_mov_b32 m0, s45
	ds_read_b128 v[186:189], v152 offset:16384
	ds_read_b128 v[190:193], v152 offset:17408
	ds_read_b128 v[194:197], v152 offset:18432
	ds_read_b128 v[198:201], v152 offset:19456
	ds_read_b128 v[202:205], v152 offset:20480
	ds_read_b128 v[206:209], v152 offset:21504
	ds_read_b128 v[210:213], v152 offset:22528
	ds_read_b128 v[214:217], v152 offset:23552
	global_load_lds_dwordx4 v134, s[22:23]
	s_add_i32 m0, s45, 0x2000
	s_add_u32 s46, s22, 0x40000
	s_addc_u32 s47, s23, 0
	s_add_i32 s45, s36, s26
	global_load_lds_dwordx4 v130, s[22:23]
	s_mov_b32 m0, s45
	s_nop 0
	global_load_lds_dwordx4 v134, s[46:47]
	s_add_i32 m0, s45, 0x2000
	s_nop 0
	global_load_lds_dwordx4 v130, s[46:47]
	s_mov_b32 m0, s27
	s_nop 0
	global_load_lds_dwordx4 v136, s[24:25]
	s_mov_b32 m0, s28
	s_nop 0
	global_load_lds_dwordx4 v132, s[24:25]
	s_waitcnt vmcnt(8)
	s_waitcnt lgkmcnt(0)
	s_barrier
	s_setprio 1
	v_mfma_f32_16x16x32_bf16 v[62:65], v[154:157], v[186:189], 0
	v_mfma_f32_16x16x32_bf16 v[62:65], v[158:161], v[190:193], v[62:65]
	v_mfma_f32_16x16x32_bf16 v[54:57], v[162:165], v[186:189], 0
	v_mfma_f32_16x16x32_bf16 v[54:57], v[166:169], v[190:193], v[54:57]
	v_mfma_f32_16x16x32_bf16 v[38:41], v[162:165], v[194:197], 0
	v_mfma_f32_16x16x32_bf16 v[38:41], v[166:169], v[198:201], v[38:41]
	v_mfma_f32_16x16x32_bf16 v[46:49], v[154:157], v[194:197], 0
	v_mfma_f32_16x16x32_bf16 v[46:49], v[158:161], v[198:201], v[46:49]
	v_mfma_f32_16x16x32_bf16 v[30:33], v[154:157], v[202:205], 0
	v_mfma_f32_16x16x32_bf16 v[30:33], v[158:161], v[206:209], v[30:33]
	v_mfma_f32_16x16x32_bf16 v[22:25], v[162:165], v[202:205], 0
	v_mfma_f32_16x16x32_bf16 v[22:25], v[166:169], v[206:209], v[22:25]
	v_mfma_f32_16x16x32_bf16 v[6:9], v[162:165], v[210:213], 0
	v_mfma_f32_16x16x32_bf16 v[6:9], v[166:169], v[214:217], v[6:9]
	v_mfma_f32_16x16x32_bf16 v[14:17], v[154:157], v[210:213], 0
	v_mfma_f32_16x16x32_bf16 v[14:17], v[158:161], v[214:217], v[14:17]
	v_mfma_f32_16x16x32_bf16 v[58:61], v[170:173], v[186:189], 0
	v_mfma_f32_16x16x32_bf16 v[58:61], v[174:177], v[190:193], v[58:61]
	v_mfma_f32_16x16x32_bf16 v[50:53], v[178:181], v[186:189], 0
	v_mfma_f32_16x16x32_bf16 v[50:53], v[182:185], v[190:193], v[50:53]
	v_mfma_f32_16x16x32_bf16 v[34:37], v[178:181], v[194:197], 0
	v_mfma_f32_16x16x32_bf16 v[34:37], v[182:185], v[198:201], v[34:37]
	v_mfma_f32_16x16x32_bf16 v[42:45], v[170:173], v[194:197], 0
	v_mfma_f32_16x16x32_bf16 v[42:45], v[174:177], v[198:201], v[42:45]
	v_mfma_f32_16x16x32_bf16 v[26:29], v[170:173], v[202:205], 0
	v_mfma_f32_16x16x32_bf16 v[26:29], v[174:177], v[206:209], v[26:29]
	v_mfma_f32_16x16x32_bf16 v[18:21], v[178:181], v[202:205], 0
	v_mfma_f32_16x16x32_bf16 v[18:21], v[182:185], v[206:209], v[18:21]
	s_setprio 2
	s_barrier
	v_mfma_f32_16x16x32_bf16 v[2:5], v[178:181], v[210:213], 0
	v_mfma_f32_16x16x32_bf16 v[2:5], v[182:185], v[214:217], v[2:5]
	v_mfma_f32_16x16x32_bf16 v[10:13], v[170:173], v[210:213], 0
	v_mfma_f32_16x16x32_bf16 v[10:13], v[174:177], v[214:217], v[10:13]
	s_setprio 0
	s_nop 0
	s_add_i32 s45, 0, 0x18000
	s_add_i32 s46, 0, 0x1c000
	ds_read_b128 v[154:157], v229 offset:32768
	ds_read_b128 v[158:161], v229 offset:33792
	ds_read_b128 v[162:165], v229 offset:34816
	ds_read_b128 v[166:169], v229 offset:35840
	ds_read_b128 v[170:173], v229 offset:49152
	ds_read_b128 v[174:177], v229 offset:50176
	ds_read_b128 v[178:181], v229 offset:51200
	ds_read_b128 v[182:185], v229 offset:52224
	s_add_u32 s24, s24, 0x40000
	s_addc_u32 s25, s25, 0
	s_mov_b32 m0, s29
	ds_read_b128 v[186:189], v152 offset:32768
	ds_read_b128 v[190:193], v152 offset:33792
	ds_read_b128 v[194:197], v152 offset:34816
	ds_read_b128 v[198:201], v152 offset:35840
	ds_read_b128 v[202:205], v152 offset:36864
	ds_read_b128 v[206:209], v152 offset:37888
	ds_read_b128 v[210:213], v152 offset:38912
	ds_read_b128 v[214:217], v152 offset:39936
	global_load_lds_dwordx4 v136, s[24:25]
	s_mov_b32 m0, s30
	s_nop 0
	global_load_lds_dwordx4 v132, s[24:25]
	s_waitcnt vmcnt(8)
	s_waitcnt lgkmcnt(0)
	s_barrier
	s_setprio 1
	v_mfma_f32_16x16x32_bf16 v[126:129], v[154:157], v[186:189], v[126:129]
	v_mfma_f32_16x16x32_bf16 v[126:129], v[158:161], v[190:193], v[126:129]
	v_mfma_f32_16x16x32_bf16 v[118:121], v[162:165], v[186:189], v[118:121]
	v_mfma_f32_16x16x32_bf16 v[118:121], v[166:169], v[190:193], v[118:121]
	v_mfma_f32_16x16x32_bf16 v[102:105], v[162:165], v[194:197], v[102:105]
	v_mfma_f32_16x16x32_bf16 v[102:105], v[166:169], v[198:201], v[102:105]
	v_mfma_f32_16x16x32_bf16 v[110:113], v[154:157], v[194:197], v[110:113]
	v_mfma_f32_16x16x32_bf16 v[110:113], v[158:161], v[198:201], v[110:113]
	v_mfma_f32_16x16x32_bf16 v[94:97], v[154:157], v[202:205], v[94:97]
	v_mfma_f32_16x16x32_bf16 v[94:97], v[158:161], v[206:209], v[94:97]
	v_mfma_f32_16x16x32_bf16 v[86:89], v[162:165], v[202:205], v[86:89]
	v_mfma_f32_16x16x32_bf16 v[86:89], v[166:169], v[206:209], v[86:89]
	v_mfma_f32_16x16x32_bf16 v[70:73], v[162:165], v[210:213], v[70:73]
	v_mfma_f32_16x16x32_bf16 v[70:73], v[166:169], v[214:217], v[70:73]
	v_mfma_f32_16x16x32_bf16 v[78:81], v[154:157], v[210:213], v[78:81]
	v_mfma_f32_16x16x32_bf16 v[78:81], v[158:161], v[214:217], v[78:81]
	v_mfma_f32_16x16x32_bf16 v[122:125], v[170:173], v[186:189], v[122:125]
	v_mfma_f32_16x16x32_bf16 v[122:125], v[174:177], v[190:193], v[122:125]
	v_mfma_f32_16x16x32_bf16 v[114:117], v[178:181], v[186:189], v[114:117]
	v_mfma_f32_16x16x32_bf16 v[114:117], v[182:185], v[190:193], v[114:117]
	v_mfma_f32_16x16x32_bf16 v[98:101], v[178:181], v[194:197], v[98:101]
	v_mfma_f32_16x16x32_bf16 v[98:101], v[182:185], v[198:201], v[98:101]
	v_mfma_f32_16x16x32_bf16 v[106:109], v[170:173], v[194:197], v[106:109]
	v_mfma_f32_16x16x32_bf16 v[106:109], v[174:177], v[198:201], v[106:109]
	v_mfma_f32_16x16x32_bf16 v[90:93], v[170:173], v[202:205], v[90:93]
	v_mfma_f32_16x16x32_bf16 v[90:93], v[174:177], v[206:209], v[90:93]
	v_mfma_f32_16x16x32_bf16 v[82:85], v[178:181], v[202:205], v[82:85]
	v_mfma_f32_16x16x32_bf16 v[82:85], v[182:185], v[206:209], v[82:85]
	s_setprio 2
	s_barrier
	v_mfma_f32_16x16x32_bf16 v[66:69], v[178:181], v[210:213], v[66:69]
	v_mfma_f32_16x16x32_bf16 v[66:69], v[182:185], v[214:217], v[66:69]
	v_mfma_f32_16x16x32_bf16 v[74:77], v[170:173], v[210:213], v[74:77]
	v_mfma_f32_16x16x32_bf16 v[74:77], v[174:177], v[214:217], v[74:77]
	s_setprio 0
	s_nop 0
	s_add_i32 s24, s45, s26
	s_mov_b32 m0, s24
	ds_read_b128 v[186:189], v152 offset:49152
	ds_read_b128 v[190:193], v152 offset:50176
	ds_read_b128 v[194:197], v152 offset:51200
	ds_read_b128 v[198:201], v152 offset:52224
	ds_read_b128 v[202:205], v152 offset:53248
	ds_read_b128 v[206:209], v152 offset:54272
	ds_read_b128 v[210:213], v152 offset:55296
	ds_read_b128 v[214:217], v152 offset:56320
	global_load_lds_dwordx4 v134, s[50:51]
	s_add_i32 m0, s24, 0x2000
	s_add_u32 s22, s22, 0x40080
	s_addc_u32 s23, s23, 0
	s_add_i32 s24, s46, s26
	global_load_lds_dwordx4 v130, s[50:51]
	s_mov_b32 m0, s24
	s_nop 0
	global_load_lds_dwordx4 v134, s[22:23]
	s_add_i32 m0, s24, 0x2000
	s_nop 0
	global_load_lds_dwordx4 v130, s[22:23]
	s_mov_b32 m0, s33
	s_nop 0
	global_load_lds_dwordx4 v136, s[52:53]
	s_mov_b32 m0, s34
	s_nop 0
	global_load_lds_dwordx4 v132, s[52:53]
	s_waitcnt vmcnt(8)
	s_waitcnt lgkmcnt(0)
	s_barrier
	s_setprio 1
	v_mfma_f32_16x16x32_bf16 v[62:65], v[154:157], v[186:189], v[62:65]
	v_mfma_f32_16x16x32_bf16 v[62:65], v[158:161], v[190:193], v[62:65]
	v_mfma_f32_16x16x32_bf16 v[54:57], v[162:165], v[186:189], v[54:57]
	v_mfma_f32_16x16x32_bf16 v[54:57], v[166:169], v[190:193], v[54:57]
	v_mfma_f32_16x16x32_bf16 v[38:41], v[162:165], v[194:197], v[38:41]
	v_mfma_f32_16x16x32_bf16 v[38:41], v[166:169], v[198:201], v[38:41]
	v_mfma_f32_16x16x32_bf16 v[46:49], v[154:157], v[194:197], v[46:49]
	v_mfma_f32_16x16x32_bf16 v[46:49], v[158:161], v[198:201], v[46:49]
	v_mfma_f32_16x16x32_bf16 v[30:33], v[154:157], v[202:205], v[30:33]
	v_mfma_f32_16x16x32_bf16 v[30:33], v[158:161], v[206:209], v[30:33]
	v_mfma_f32_16x16x32_bf16 v[22:25], v[162:165], v[202:205], v[22:25]
	v_mfma_f32_16x16x32_bf16 v[22:25], v[166:169], v[206:209], v[22:25]
	v_mfma_f32_16x16x32_bf16 v[6:9], v[162:165], v[210:213], v[6:9]
	v_mfma_f32_16x16x32_bf16 v[6:9], v[166:169], v[214:217], v[6:9]
	v_mfma_f32_16x16x32_bf16 v[14:17], v[154:157], v[210:213], v[14:17]
	v_mfma_f32_16x16x32_bf16 v[14:17], v[158:161], v[214:217], v[14:17]
	v_mfma_f32_16x16x32_bf16 v[58:61], v[170:173], v[186:189], v[58:61]
	v_mfma_f32_16x16x32_bf16 v[58:61], v[174:177], v[190:193], v[58:61]
	v_mfma_f32_16x16x32_bf16 v[50:53], v[178:181], v[186:189], v[50:53]
	v_mfma_f32_16x16x32_bf16 v[50:53], v[182:185], v[190:193], v[50:53]
	v_mfma_f32_16x16x32_bf16 v[34:37], v[178:181], v[194:197], v[34:37]
	v_mfma_f32_16x16x32_bf16 v[34:37], v[182:185], v[198:201], v[34:37]
	v_mfma_f32_16x16x32_bf16 v[42:45], v[170:173], v[194:197], v[42:45]
	v_mfma_f32_16x16x32_bf16 v[42:45], v[174:177], v[198:201], v[42:45]
	v_mfma_f32_16x16x32_bf16 v[26:29], v[170:173], v[202:205], v[26:29]
	v_mfma_f32_16x16x32_bf16 v[26:29], v[174:177], v[206:209], v[26:29]
	v_mfma_f32_16x16x32_bf16 v[18:21], v[178:181], v[202:205], v[18:21]
	v_mfma_f32_16x16x32_bf16 v[18:21], v[182:185], v[206:209], v[18:21]
	s_setprio 2
	s_barrier
	v_mfma_f32_16x16x32_bf16 v[2:5], v[178:181], v[210:213], v[2:5]
	v_mfma_f32_16x16x32_bf16 v[2:5], v[182:185], v[214:217], v[2:5]
	v_mfma_f32_16x16x32_bf16 v[10:13], v[170:173], v[210:213], v[10:13]
	v_mfma_f32_16x16x32_bf16 v[10:13], v[174:177], v[214:217], v[10:13]
	s_setprio 0
	s_nop 0
	s_add_i32 s44, s44, 2
	s_add_u32 s20, s20, 0x100
	s_addc_u32 s21, s21, 0
	s_cmp_gt_u32 s44, 13
	s_cbranch_scc1 .LBB0_948
	s_branch .LBB0_946
.LBB0_945:
	ds_read_b128 v[154:157], v229
	ds_read_b128 v[158:161], v229 offset:1024
	ds_read_b128 v[162:165], v229 offset:2048
	ds_read_b128 v[166:169], v229 offset:3072
	s_add_u32 s22, s18, s20
	ds_read_b128 v[170:173], v229 offset:16384
	ds_read_b128 v[174:177], v229 offset:17408
	ds_read_b128 v[178:181], v229 offset:18432
	ds_read_b128 v[182:185], v229 offset:19456
	s_addc_u32 s23, s19, s21
	s_add_u32 s22, s22, 0x100
	s_addc_u32 s23, s23, 0
	s_add_u32 s45, s42, s20
	s_addc_u32 s46, s43, s21
	s_cmpk_eq_i32 s20, 0x700
	s_cselect_b32 s25, s9, s23
	s_cselect_b32 s24, s39, s22
	s_cselect_b32 s23, s40, s46
	s_cselect_b32 s22, s41, s45
	s_add_u32 s48, s18, s20
	s_addc_u32 s49, s19, s21
	s_add_i32 m0, s27, 0xc000
	ds_read_b128 v[186:189], v152
	ds_read_b128 v[190:193], v152 offset:1024
	ds_read_b128 v[194:197], v152 offset:2048
	ds_read_b128 v[198:201], v152 offset:3072
	ds_read_b128 v[202:205], v152 offset:4096
	ds_read_b128 v[206:209], v152 offset:5120
	ds_read_b128 v[210:213], v152 offset:6144
	ds_read_b128 v[214:217], v152 offset:7168
	global_load_lds_dwordx4 v138, s[48:49]
	s_add_i32 m0, s27, 0xe000
	s_nop 0
	global_load_lds_dwordx4 v140, s[48:49]
	s_waitcnt vmcnt(8)
	s_waitcnt lgkmcnt(0)
	s_barrier
	s_setprio 1
	v_mfma_f32_16x16x32_bf16 v[126:129], v[154:157], v[186:189], v[126:129]
	v_mfma_f32_16x16x32_bf16 v[126:129], v[158:161], v[190:193], v[126:129]
	v_mfma_f32_16x16x32_bf16 v[118:121], v[162:165], v[186:189], v[118:121]
	v_mfma_f32_16x16x32_bf16 v[118:121], v[166:169], v[190:193], v[118:121]
	v_mfma_f32_16x16x32_bf16 v[102:105], v[162:165], v[194:197], v[102:105]
	v_mfma_f32_16x16x32_bf16 v[102:105], v[166:169], v[198:201], v[102:105]
	v_mfma_f32_16x16x32_bf16 v[110:113], v[154:157], v[194:197], v[110:113]
	v_mfma_f32_16x16x32_bf16 v[110:113], v[158:161], v[198:201], v[110:113]
	v_mfma_f32_16x16x32_bf16 v[94:97], v[154:157], v[202:205], v[94:97]
	v_mfma_f32_16x16x32_bf16 v[94:97], v[158:161], v[206:209], v[94:97]
	v_mfma_f32_16x16x32_bf16 v[86:89], v[162:165], v[202:205], v[86:89]
	v_mfma_f32_16x16x32_bf16 v[86:89], v[166:169], v[206:209], v[86:89]
	v_mfma_f32_16x16x32_bf16 v[70:73], v[162:165], v[210:213], v[70:73]
	v_mfma_f32_16x16x32_bf16 v[70:73], v[166:169], v[214:217], v[70:73]
	v_mfma_f32_16x16x32_bf16 v[78:81], v[154:157], v[210:213], v[78:81]
	v_mfma_f32_16x16x32_bf16 v[78:81], v[158:161], v[214:217], v[78:81]
	v_mfma_f32_16x16x32_bf16 v[122:125], v[170:173], v[186:189], v[122:125]
	v_mfma_f32_16x16x32_bf16 v[122:125], v[174:177], v[190:193], v[122:125]
	v_mfma_f32_16x16x32_bf16 v[114:117], v[178:181], v[186:189], v[114:117]
	v_mfma_f32_16x16x32_bf16 v[114:117], v[182:185], v[190:193], v[114:117]
	v_mfma_f32_16x16x32_bf16 v[98:101], v[178:181], v[194:197], v[98:101]
	v_mfma_f32_16x16x32_bf16 v[98:101], v[182:185], v[198:201], v[98:101]
	v_mfma_f32_16x16x32_bf16 v[106:109], v[170:173], v[194:197], v[106:109]
	v_mfma_f32_16x16x32_bf16 v[106:109], v[174:177], v[198:201], v[106:109]
	v_mfma_f32_16x16x32_bf16 v[90:93], v[170:173], v[202:205], v[90:93]
	v_mfma_f32_16x16x32_bf16 v[90:93], v[174:177], v[206:209], v[90:93]
	v_mfma_f32_16x16x32_bf16 v[82:85], v[178:181], v[202:205], v[82:85]
	v_mfma_f32_16x16x32_bf16 v[82:85], v[182:185], v[206:209], v[82:85]
	s_setprio 2
	s_barrier
	v_mfma_f32_16x16x32_bf16 v[66:69], v[178:181], v[210:213], v[66:69]
	v_mfma_f32_16x16x32_bf16 v[66:69], v[182:185], v[214:217], v[66:69]
	v_mfma_f32_16x16x32_bf16 v[74:77], v[170:173], v[210:213], v[74:77]
	v_mfma_f32_16x16x32_bf16 v[74:77], v[174:177], v[214:217], v[74:77]
	s_setprio 0
	s_nop 0
	s_add_i32 s45, s35, s26
	s_add_u32 s50, s22, 0x80
	s_addc_u32 s51, s23, 0
	s_add_u32 s52, s24, 0x80
	s_addc_u32 s53, s25, 0
	s_mov_b32 m0, s45
	ds_read_b128 v[186:189], v152 offset:16384
	ds_read_b128 v[190:193], v152 offset:17408
	ds_read_b128 v[194:197], v152 offset:18432
	ds_read_b128 v[198:201], v152 offset:19456
	ds_read_b128 v[202:205], v152 offset:20480
	ds_read_b128 v[206:209], v152 offset:21504
	ds_read_b128 v[210:213], v152 offset:22528
	ds_read_b128 v[214:217], v152 offset:23552
	global_load_lds_dwordx4 v134, s[22:23]
	s_add_i32 m0, s45, 0x2000
	s_add_u32 s46, s22, 0x40000
	s_addc_u32 s47, s23, 0
	s_add_i32 s45, s36, s26
	global_load_lds_dwordx4 v130, s[22:23]
	s_mov_b32 m0, s45
	s_nop 0
	global_load_lds_dwordx4 v134, s[46:47]
	s_add_i32 m0, s45, 0x2000
	s_nop 0
	global_load_lds_dwordx4 v130, s[46:47]
	s_mov_b32 m0, s27
	s_nop 0
	global_load_lds_dwordx4 v136, s[24:25]
	s_mov_b32 m0, s28
	s_nop 0
	global_load_lds_dwordx4 v132, s[24:25]
	s_waitcnt vmcnt(8)
	s_waitcnt lgkmcnt(0)
	s_barrier
	s_setprio 1
	v_mfma_f32_16x16x32_bf16 v[62:65], v[154:157], v[186:189], v[62:65]
	v_mfma_f32_16x16x32_bf16 v[62:65], v[158:161], v[190:193], v[62:65]
	v_mfma_f32_16x16x32_bf16 v[54:57], v[162:165], v[186:189], v[54:57]
	v_mfma_f32_16x16x32_bf16 v[54:57], v[166:169], v[190:193], v[54:57]
	v_mfma_f32_16x16x32_bf16 v[38:41], v[162:165], v[194:197], v[38:41]
	v_mfma_f32_16x16x32_bf16 v[38:41], v[166:169], v[198:201], v[38:41]
	v_mfma_f32_16x16x32_bf16 v[46:49], v[154:157], v[194:197], v[46:49]
	v_mfma_f32_16x16x32_bf16 v[46:49], v[158:161], v[198:201], v[46:49]
	v_mfma_f32_16x16x32_bf16 v[30:33], v[154:157], v[202:205], v[30:33]
	v_mfma_f32_16x16x32_bf16 v[30:33], v[158:161], v[206:209], v[30:33]
	v_mfma_f32_16x16x32_bf16 v[22:25], v[162:165], v[202:205], v[22:25]
	v_mfma_f32_16x16x32_bf16 v[22:25], v[166:169], v[206:209], v[22:25]
	v_mfma_f32_16x16x32_bf16 v[6:9], v[162:165], v[210:213], v[6:9]
	v_mfma_f32_16x16x32_bf16 v[6:9], v[166:169], v[214:217], v[6:9]
	v_mfma_f32_16x16x32_bf16 v[14:17], v[154:157], v[210:213], v[14:17]
	v_mfma_f32_16x16x32_bf16 v[14:17], v[158:161], v[214:217], v[14:17]
	v_mfma_f32_16x16x32_bf16 v[58:61], v[170:173], v[186:189], v[58:61]
	v_mfma_f32_16x16x32_bf16 v[58:61], v[174:177], v[190:193], v[58:61]
	v_mfma_f32_16x16x32_bf16 v[50:53], v[178:181], v[186:189], v[50:53]
	v_mfma_f32_16x16x32_bf16 v[50:53], v[182:185], v[190:193], v[50:53]
	v_mfma_f32_16x16x32_bf16 v[34:37], v[178:181], v[194:197], v[34:37]
	v_mfma_f32_16x16x32_bf16 v[34:37], v[182:185], v[198:201], v[34:37]
	v_mfma_f32_16x16x32_bf16 v[42:45], v[170:173], v[194:197], v[42:45]
	v_mfma_f32_16x16x32_bf16 v[42:45], v[174:177], v[198:201], v[42:45]
	v_mfma_f32_16x16x32_bf16 v[26:29], v[170:173], v[202:205], v[26:29]
	v_mfma_f32_16x16x32_bf16 v[26:29], v[174:177], v[206:209], v[26:29]
	v_mfma_f32_16x16x32_bf16 v[18:21], v[178:181], v[202:205], v[18:21]
	v_mfma_f32_16x16x32_bf16 v[18:21], v[182:185], v[206:209], v[18:21]
	s_setprio 2
	s_barrier
	v_mfma_f32_16x16x32_bf16 v[2:5], v[178:181], v[210:213], v[2:5]
	v_mfma_f32_16x16x32_bf16 v[2:5], v[182:185], v[214:217], v[2:5]
	v_mfma_f32_16x16x32_bf16 v[10:13], v[170:173], v[210:213], v[10:13]
	v_mfma_f32_16x16x32_bf16 v[10:13], v[174:177], v[214:217], v[10:13]
	s_setprio 0
	s_nop 0
	s_add_i32 s45, 0, 0x18000
	s_add_i32 s46, 0, 0x1c000
	ds_read_b128 v[154:157], v229 offset:32768
	ds_read_b128 v[158:161], v229 offset:33792
	ds_read_b128 v[162:165], v229 offset:34816
	ds_read_b128 v[166:169], v229 offset:35840
	ds_read_b128 v[170:173], v229 offset:49152
	ds_read_b128 v[174:177], v229 offset:50176
	ds_read_b128 v[178:181], v229 offset:51200
	ds_read_b128 v[182:185], v229 offset:52224
	s_add_u32 s24, s24, 0x40000
	s_addc_u32 s25, s25, 0
	s_mov_b32 m0, s29
	ds_read_b128 v[186:189], v152 offset:32768
	ds_read_b128 v[190:193], v152 offset:33792
	ds_read_b128 v[194:197], v152 offset:34816
	ds_read_b128 v[198:201], v152 offset:35840
	ds_read_b128 v[202:205], v152 offset:36864
	ds_read_b128 v[206:209], v152 offset:37888
	ds_read_b128 v[210:213], v152 offset:38912
	ds_read_b128 v[214:217], v152 offset:39936
	global_load_lds_dwordx4 v136, s[24:25]
	s_mov_b32 m0, s30
	s_nop 0
	global_load_lds_dwordx4 v132, s[24:25]
	s_waitcnt vmcnt(8)
	s_waitcnt lgkmcnt(0)
	s_barrier
	s_setprio 1
	v_mfma_f32_16x16x32_bf16 v[126:129], v[154:157], v[186:189], v[126:129]
	v_mfma_f32_16x16x32_bf16 v[126:129], v[158:161], v[190:193], v[126:129]
	v_mfma_f32_16x16x32_bf16 v[118:121], v[162:165], v[186:189], v[118:121]
	v_mfma_f32_16x16x32_bf16 v[118:121], v[166:169], v[190:193], v[118:121]
	v_mfma_f32_16x16x32_bf16 v[102:105], v[162:165], v[194:197], v[102:105]
	v_mfma_f32_16x16x32_bf16 v[102:105], v[166:169], v[198:201], v[102:105]
	v_mfma_f32_16x16x32_bf16 v[110:113], v[154:157], v[194:197], v[110:113]
	v_mfma_f32_16x16x32_bf16 v[110:113], v[158:161], v[198:201], v[110:113]
	v_mfma_f32_16x16x32_bf16 v[94:97], v[154:157], v[202:205], v[94:97]
	v_mfma_f32_16x16x32_bf16 v[94:97], v[158:161], v[206:209], v[94:97]
	v_mfma_f32_16x16x32_bf16 v[86:89], v[162:165], v[202:205], v[86:89]
	v_mfma_f32_16x16x32_bf16 v[86:89], v[166:169], v[206:209], v[86:89]
	v_mfma_f32_16x16x32_bf16 v[70:73], v[162:165], v[210:213], v[70:73]
	v_mfma_f32_16x16x32_bf16 v[70:73], v[166:169], v[214:217], v[70:73]
	v_mfma_f32_16x16x32_bf16 v[78:81], v[154:157], v[210:213], v[78:81]
	v_mfma_f32_16x16x32_bf16 v[78:81], v[158:161], v[214:217], v[78:81]
	v_mfma_f32_16x16x32_bf16 v[122:125], v[170:173], v[186:189], v[122:125]
	v_mfma_f32_16x16x32_bf16 v[122:125], v[174:177], v[190:193], v[122:125]
	v_mfma_f32_16x16x32_bf16 v[114:117], v[178:181], v[186:189], v[114:117]
	v_mfma_f32_16x16x32_bf16 v[114:117], v[182:185], v[190:193], v[114:117]
	v_mfma_f32_16x16x32_bf16 v[98:101], v[178:181], v[194:197], v[98:101]
	v_mfma_f32_16x16x32_bf16 v[98:101], v[182:185], v[198:201], v[98:101]
	v_mfma_f32_16x16x32_bf16 v[106:109], v[170:173], v[194:197], v[106:109]
	v_mfma_f32_16x16x32_bf16 v[106:109], v[174:177], v[198:201], v[106:109]
	v_mfma_f32_16x16x32_bf16 v[90:93], v[170:173], v[202:205], v[90:93]
	v_mfma_f32_16x16x32_bf16 v[90:93], v[174:177], v[206:209], v[90:93]
	v_mfma_f32_16x16x32_bf16 v[82:85], v[178:181], v[202:205], v[82:85]
	v_mfma_f32_16x16x32_bf16 v[82:85], v[182:185], v[206:209], v[82:85]
	s_setprio 2
	s_barrier
	v_mfma_f32_16x16x32_bf16 v[66:69], v[178:181], v[210:213], v[66:69]
	v_mfma_f32_16x16x32_bf16 v[66:69], v[182:185], v[214:217], v[66:69]
	v_mfma_f32_16x16x32_bf16 v[74:77], v[170:173], v[210:213], v[74:77]
	v_mfma_f32_16x16x32_bf16 v[74:77], v[174:177], v[214:217], v[74:77]
	s_setprio 0
	s_nop 0
	s_add_i32 s24, s45, s26
	s_mov_b32 m0, s24
	ds_read_b128 v[186:189], v152 offset:49152
	ds_read_b128 v[190:193], v152 offset:50176
	ds_read_b128 v[194:197], v152 offset:51200
	ds_read_b128 v[198:201], v152 offset:52224
	ds_read_b128 v[202:205], v152 offset:53248
	ds_read_b128 v[206:209], v152 offset:54272
	ds_read_b128 v[210:213], v152 offset:55296
	ds_read_b128 v[214:217], v152 offset:56320
	global_load_lds_dwordx4 v134, s[50:51]
	s_add_i32 m0, s24, 0x2000
	s_add_u32 s22, s22, 0x40080
	s_addc_u32 s23, s23, 0
	s_add_i32 s24, s46, s26
	global_load_lds_dwordx4 v130, s[50:51]
	s_mov_b32 m0, s24
	s_nop 0
	global_load_lds_dwordx4 v134, s[22:23]
	s_add_i32 m0, s24, 0x2000
	s_nop 0
	global_load_lds_dwordx4 v130, s[22:23]
	s_mov_b32 m0, s33
	s_nop 0
	global_load_lds_dwordx4 v136, s[52:53]
	s_mov_b32 m0, s34
	s_nop 0
	global_load_lds_dwordx4 v132, s[52:53]
	s_waitcnt vmcnt(8)
	s_waitcnt lgkmcnt(0)
	s_barrier
	s_setprio 1
	v_mfma_f32_16x16x32_bf16 v[62:65], v[154:157], v[186:189], v[62:65]
	v_mfma_f32_16x16x32_bf16 v[62:65], v[158:161], v[190:193], v[62:65]
	v_mfma_f32_16x16x32_bf16 v[54:57], v[162:165], v[186:189], v[54:57]
	v_mfma_f32_16x16x32_bf16 v[54:57], v[166:169], v[190:193], v[54:57]
	v_mfma_f32_16x16x32_bf16 v[38:41], v[162:165], v[194:197], v[38:41]
	v_mfma_f32_16x16x32_bf16 v[38:41], v[166:169], v[198:201], v[38:41]
	v_mfma_f32_16x16x32_bf16 v[46:49], v[154:157], v[194:197], v[46:49]
	v_mfma_f32_16x16x32_bf16 v[46:49], v[158:161], v[198:201], v[46:49]
	v_mfma_f32_16x16x32_bf16 v[30:33], v[154:157], v[202:205], v[30:33]
	v_mfma_f32_16x16x32_bf16 v[30:33], v[158:161], v[206:209], v[30:33]
	v_mfma_f32_16x16x32_bf16 v[22:25], v[162:165], v[202:205], v[22:25]
	v_mfma_f32_16x16x32_bf16 v[22:25], v[166:169], v[206:209], v[22:25]
	v_mfma_f32_16x16x32_bf16 v[6:9], v[162:165], v[210:213], v[6:9]
	v_mfma_f32_16x16x32_bf16 v[6:9], v[166:169], v[214:217], v[6:9]
	v_mfma_f32_16x16x32_bf16 v[14:17], v[154:157], v[210:213], v[14:17]
	v_mfma_f32_16x16x32_bf16 v[14:17], v[158:161], v[214:217], v[14:17]
	v_mfma_f32_16x16x32_bf16 v[58:61], v[170:173], v[186:189], v[58:61]
	v_mfma_f32_16x16x32_bf16 v[58:61], v[174:177], v[190:193], v[58:61]
	v_mfma_f32_16x16x32_bf16 v[50:53], v[178:181], v[186:189], v[50:53]
	v_mfma_f32_16x16x32_bf16 v[50:53], v[182:185], v[190:193], v[50:53]
	v_mfma_f32_16x16x32_bf16 v[34:37], v[178:181], v[194:197], v[34:37]
	v_mfma_f32_16x16x32_bf16 v[34:37], v[182:185], v[198:201], v[34:37]
	v_mfma_f32_16x16x32_bf16 v[42:45], v[170:173], v[194:197], v[42:45]
	v_mfma_f32_16x16x32_bf16 v[42:45], v[174:177], v[198:201], v[42:45]
	v_mfma_f32_16x16x32_bf16 v[26:29], v[170:173], v[202:205], v[26:29]
	v_mfma_f32_16x16x32_bf16 v[26:29], v[174:177], v[206:209], v[26:29]
	v_mfma_f32_16x16x32_bf16 v[18:21], v[178:181], v[202:205], v[18:21]
	v_mfma_f32_16x16x32_bf16 v[18:21], v[182:185], v[206:209], v[18:21]
	s_setprio 2
	s_barrier
	v_mfma_f32_16x16x32_bf16 v[2:5], v[178:181], v[210:213], v[2:5]
	v_mfma_f32_16x16x32_bf16 v[2:5], v[182:185], v[214:217], v[2:5]
	v_mfma_f32_16x16x32_bf16 v[10:13], v[170:173], v[210:213], v[10:13]
	v_mfma_f32_16x16x32_bf16 v[10:13], v[174:177], v[214:217], v[10:13]
	s_setprio 0
	s_nop 0
	s_add_i32 s44, s44, 2
	s_add_u32 s20, s20, 0x100
	s_addc_u32 s21, s21, 0
	s_cmp_gt_u32 s44, 13
	s_cbranch_scc1 .LBB0_948

.LBB0_1017:
	v_lshl_add_u64 v[14:15], s[14:15], 0, v[130:131]
	v_lshl_add_u64 v[16:17], s[14:15], 0, v[134:135]
	s_add_i32 m0, s50, 0x18000
	v_lshl_add_u64 v[14:15], v[14:15], 0, s[24:25]
	s_waitcnt vmcnt(2)
	s_barrier
	global_load_lds_dwordx4 v[14:15], off
	v_lshl_add_u64 v[14:15], v[16:17], 0, s[24:25]
	s_add_i32 m0, s50, 0x1a000
	s_add_i32 s54, s50, 0x8000
	global_load_lds_dwordx4 v[14:15], off
	v_lshl_add_u64 v[4:5], v[4:5], 0, s[24:25]
	s_mov_b32 m0, s54
	s_add_i32 s55, s50, 0xa000
	global_load_lds_dwordx4 v[4:5], off
	v_lshl_add_u64 v[2:3], v[2:3], 0, s[24:25]
	s_mov_b32 m0, s55
	v_and_b32_e32 v212, 15, v211
	global_load_lds_dwordx4 v[2:3], off
	s_add_i32 m0, s50, 0x1c000
	v_lshl_add_u64 v[2:3], s[18:19], 0, v[130:131]
	global_load_lds_dwordx4 v[2:3], off
	v_lshl_add_u64 v[2:3], s[18:19], 0, v[134:135]
	s_add_i32 m0, s50, 0x1e000
	v_and_b32_e32 v18, 48, v211
	global_load_lds_dwordx4 v[2:3], off
	v_lshlrev_b32_e32 v19, 2, v211
	s_and_b32 s38, s34, 3
	s_lshl_b32 s4, s35, 13
	v_lshl_or_b32 v18, v212, 6, v18
	v_and_b32_e32 v19, 32, v19
	v_bitop3_b32 v20, v18, s4, v19 bitop3:0xde
	s_lshl_b32 s4, s38, 12
	s_add_u32 s56, s42, s3
	s_addc_u32 s57, s43, s2
	v_bitop3_b32 v140, v18, s4, v19 bitop3:0xde
	s_add_u32 s4, s44, s3
	v_lshrrev_b32_e32 v3, 1, v11
	v_mul_lo_u32 v2, v10, s46
	s_addc_u32 s5, s45, s2
	v_mad_u64_u32 v[2:3], s[2:3], v3, s47, v[2:3]
	v_or_b32_e32 v2, v2, v12
	v_add_lshl_u32 v2, v2, v13, 1
	v_mov_b32_e32 v3, v131
	v_lshl_add_u64 v[136:137], s[4:5], 0, v[2:3]
	v_lshrrev_b32_e32 v3, 1, v6
	v_mul_lo_u32 v2, v7, s46
	v_mad_u64_u32 v[2:3], s[2:3], v3, s47, v[2:3]
	v_or_b32_e32 v2, v2, v8
	s_waitcnt vmcnt(6)
	v_add_lshl_u32 v2, v2, v9, 1
	v_mov_b32_e32 v3, v131
	v_lshl_add_u64 v[138:139], s[4:5], 0, v[2:3]
	v_mov_b32_e32 v2, 0
	v_lshl_or_b32 v210, s35, 6, v212
	s_mov_b32 s58, -2
	v_add_u32_e32 v141, 0, v20
	s_mov_b64 s[2:3], s[22:23]
	s_barrier
	s_add_u32 s4, s70, s56
	s_addc_u32 s5, s71, s57
	s_add_u32 s59, s70, s2
	s_addc_u32 s60, s71, s3
	s_add_i32 s61, 0, 0x10000
	s_cmp_eq_u32 s58, 40
	s_cselect_b32 s31, s1, s5
	s_cselect_b32 s30, s0, s4
	s_cselect_b32 s5, s15, s60
	s_cselect_b32 s4, s14, s59
	s_add_i32 s59, 0, 0x14000
	v_add_u32_e32 v154, s61, v140
	v_add_u32_e32 v170, s59, v140
	ds_read_b128 v[142:145], v154
	ds_read_b128 v[146:149], v154 offset:1024
	ds_read_b128 v[150:153], v154 offset:2048
	ds_read_b128 v[154:157], v154 offset:3072
	ds_read_b128 v[158:161], v170
	ds_read_b128 v[162:165], v170 offset:1024
	ds_read_b128 v[166:169], v170 offset:2048
	ds_read_b128 v[170:173], v170 offset:3072
	v_lshl_add_u64 v[214:215], s[70:71], 0, v[136:137]
	s_add_i32 m0, s50, 0xc000
	ds_read_b128 v[174:177], v141
	ds_read_b128 v[178:181], v141 offset:1024
	ds_read_b128 v[182:185], v141 offset:2048
	ds_read_b128 v[186:189], v141 offset:3072
	ds_read_b128 v[190:193], v141 offset:4096
	ds_read_b128 v[194:197], v141 offset:5120
	ds_read_b128 v[198:201], v141 offset:6144
	ds_read_b128 v[202:205], v141 offset:7168
	global_load_lds_dwordx4 v[214:215], off
	v_lshl_add_u64 v[214:215], s[70:71], 0, v[138:139]
	s_add_i32 m0, s50, 0xe000
	s_nop 0
	global_load_lds_dwordx4 v[214:215], off
	s_waitcnt vmcnt(8)
	s_waitcnt lgkmcnt(0)
	s_barrier
	s_setprio 1
	v_mfma_f32_16x16x32_bf16 v[126:129], v[142:145], v[174:177], 0
	v_mfma_f32_16x16x32_bf16 v[126:129], v[146:149], v[178:181], v[126:129]
	v_mfma_f32_16x16x32_bf16 v[122:125], v[150:153], v[174:177], 0
	v_mfma_f32_16x16x32_bf16 v[122:125], v[154:157], v[178:181], v[122:125]
	v_mfma_f32_16x16x32_bf16 v[106:109], v[150:153], v[182:185], 0
	v_mfma_f32_16x16x32_bf16 v[106:109], v[154:157], v[186:189], v[106:109]
	v_mfma_f32_16x16x32_bf16 v[110:113], v[142:145], v[182:185], 0
	v_mfma_f32_16x16x32_bf16 v[110:113], v[146:149], v[186:189], v[110:113]
	v_mfma_f32_16x16x32_bf16 v[94:97], v[142:145], v[190:193], 0
	v_mfma_f32_16x16x32_bf16 v[94:97], v[146:149], v[194:197], v[94:97]
	v_mfma_f32_16x16x32_bf16 v[90:93], v[150:153], v[190:193], 0
	v_mfma_f32_16x16x32_bf16 v[90:93], v[154:157], v[194:197], v[90:93]
	v_mfma_f32_16x16x32_bf16 v[74:77], v[150:153], v[198:201], 0
	v_mfma_f32_16x16x32_bf16 v[74:77], v[154:157], v[202:205], v[74:77]
	v_mfma_f32_16x16x32_bf16 v[78:81], v[142:145], v[198:201], 0
	v_mfma_f32_16x16x32_bf16 v[78:81], v[146:149], v[202:205], v[78:81]
	v_mfma_f32_16x16x32_bf16 v[118:121], v[158:161], v[174:177], 0
	v_mfma_f32_16x16x32_bf16 v[118:121], v[162:165], v[178:181], v[118:121]
	v_mfma_f32_16x16x32_bf16 v[114:117], v[166:169], v[174:177], 0
	v_mfma_f32_16x16x32_bf16 v[114:117], v[170:173], v[178:181], v[114:117]
	v_mfma_f32_16x16x32_bf16 v[98:101], v[166:169], v[182:185], 0
	v_mfma_f32_16x16x32_bf16 v[98:101], v[170:173], v[186:189], v[98:101]
	v_mfma_f32_16x16x32_bf16 v[102:105], v[158:161], v[182:185], 0
	v_mfma_f32_16x16x32_bf16 v[102:105], v[162:165], v[186:189], v[102:105]
	v_mfma_f32_16x16x32_bf16 v[86:89], v[158:161], v[190:193], 0
	v_mfma_f32_16x16x32_bf16 v[86:89], v[162:165], v[194:197], v[86:89]
	v_mfma_f32_16x16x32_bf16 v[82:85], v[166:169], v[190:193], 0
	v_mfma_f32_16x16x32_bf16 v[82:85], v[170:173], v[194:197], v[82:85]
	s_setprio 2
	s_barrier
	v_mfma_f32_16x16x32_bf16 v[66:69], v[166:169], v[198:201], 0
	v_mfma_f32_16x16x32_bf16 v[66:69], v[170:173], v[202:205], v[66:69]
	v_mfma_f32_16x16x32_bf16 v[70:73], v[158:161], v[198:201], 0
	v_mfma_f32_16x16x32_bf16 v[70:73], v[162:165], v[202:205], v[70:73]
	s_setprio 0
	s_nop 0
	s_add_i32 s60, s61, s39
	v_lshl_add_u64 v[214:215], s[4:5], 0, v[130:131]
	s_mov_b32 m0, s60
	ds_read_b128 v[174:177], v141 offset:16384
	ds_read_b128 v[178:181], v141 offset:17408
	ds_read_b128 v[182:185], v141 offset:18432
	ds_read_b128 v[186:189], v141 offset:19456
	ds_read_b128 v[190:193], v141 offset:20480
	ds_read_b128 v[194:197], v141 offset:21504
	ds_read_b128 v[198:201], v141 offset:22528
	ds_read_b128 v[202:205], v141 offset:23552
	global_load_lds_dwordx4 v[214:215], off
	s_add_i32 m0, s60, 0x2000
	s_add_u32 s60, s4, 0xb0000
	v_lshl_add_u64 v[216:217], s[4:5], 0, v[134:135]
	s_addc_u32 s61, s5, 0
	s_add_i32 s59, s59, s39
	global_load_lds_dwordx4 v[216:217], off
	v_lshl_add_u64 v[218:219], s[60:61], 0, v[130:131]
	s_mov_b32 m0, s59
	v_lshl_add_u64 v[220:221], s[30:31], 0, v[134:135]
	global_load_lds_dwordx4 v[218:219], off
	v_lshl_add_u64 v[218:219], s[60:61], 0, v[134:135]
	s_add_i32 m0, s59, 0x2000
	s_nop 0
	global_load_lds_dwordx4 v[218:219], off
	v_lshl_add_u64 v[218:219], s[30:31], 0, v[130:131]
	s_mov_b32 m0, s50
	s_nop 0
	global_load_lds_dwordx4 v[218:219], off
	s_mov_b32 m0, s51
	s_nop 0
	global_load_lds_dwordx4 v[220:221], off
	s_waitcnt vmcnt(8)
	s_waitcnt lgkmcnt(0)
	s_barrier
	s_setprio 1
	v_mfma_f32_16x16x32_bf16 v[62:65], v[142:145], v[174:177], 0
	v_mfma_f32_16x16x32_bf16 v[62:65], v[146:149], v[178:181], v[62:65]
	v_mfma_f32_16x16x32_bf16 v[58:61], v[150:153], v[174:177], 0
	v_mfma_f32_16x16x32_bf16 v[58:61], v[154:157], v[178:181], v[58:61]
	v_mfma_f32_16x16x32_bf16 v[42:45], v[150:153], v[182:185], 0
	v_mfma_f32_16x16x32_bf16 v[42:45], v[154:157], v[186:189], v[42:45]
	v_mfma_f32_16x16x32_bf16 v[46:49], v[142:145], v[182:185], 0
	v_mfma_f32_16x16x32_bf16 v[46:49], v[146:149], v[186:189], v[46:49]
	v_mfma_f32_16x16x32_bf16 v[30:33], v[142:145], v[190:193], 0
	v_mfma_f32_16x16x32_bf16 v[30:33], v[146:149], v[194:197], v[30:33]
	v_mfma_f32_16x16x32_bf16 v[26:29], v[150:153], v[190:193], 0
	v_mfma_f32_16x16x32_bf16 v[26:29], v[154:157], v[194:197], v[26:29]
	v_mfma_f32_16x16x32_bf16 v[10:13], v[150:153], v[198:201], 0
	v_mfma_f32_16x16x32_bf16 v[10:13], v[154:157], v[202:205], v[10:13]
	v_mfma_f32_16x16x32_bf16 v[14:17], v[142:145], v[198:201], 0
	v_mfma_f32_16x16x32_bf16 v[14:17], v[146:149], v[202:205], v[14:17]
	v_mfma_f32_16x16x32_bf16 v[54:57], v[158:161], v[174:177], 0
	v_mfma_f32_16x16x32_bf16 v[54:57], v[162:165], v[178:181], v[54:57]
	v_mfma_f32_16x16x32_bf16 v[50:53], v[166:169], v[174:177], 0
	v_mfma_f32_16x16x32_bf16 v[50:53], v[170:173], v[178:181], v[50:53]
	v_mfma_f32_16x16x32_bf16 v[34:37], v[166:169], v[182:185], 0
	v_mfma_f32_16x16x32_bf16 v[34:37], v[170:173], v[186:189], v[34:37]
	v_mfma_f32_16x16x32_bf16 v[38:41], v[158:161], v[182:185], 0
	v_mfma_f32_16x16x32_bf16 v[38:41], v[162:165], v[186:189], v[38:41]
	v_mfma_f32_16x16x32_bf16 v[22:25], v[158:161], v[190:193], 0
	v_mfma_f32_16x16x32_bf16 v[22:25], v[162:165], v[194:197], v[22:25]
	v_mfma_f32_16x16x32_bf16 v[18:21], v[166:169], v[190:193], 0
	v_mfma_f32_16x16x32_bf16 v[18:21], v[170:173], v[194:197], v[18:21]
	s_setprio 2
	s_barrier
	v_mfma_f32_16x16x32_bf16 v[2:5], v[166:169], v[198:201], 0
	v_mfma_f32_16x16x32_bf16 v[2:5], v[170:173], v[202:205], v[2:5]
	v_mfma_f32_16x16x32_bf16 v[6:9], v[158:161], v[198:201], 0
	v_mfma_f32_16x16x32_bf16 v[6:9], v[162:165], v[202:205], v[6:9]
	s_setprio 0
	s_nop 0
	s_add_i32 s59, 0, 0x18000
	s_add_i32 s60, 0, 0x1c000
	v_add_u32_e32 v154, s59, v140
	v_add_u32_e32 v170, s60, v140
	ds_read_b128 v[142:145], v154
	ds_read_b128 v[146:149], v154 offset:1024
	ds_read_b128 v[150:153], v154 offset:2048
	ds_read_b128 v[154:157], v154 offset:3072
	ds_read_b128 v[158:161], v170
	ds_read_b128 v[162:165], v170 offset:1024
	ds_read_b128 v[166:169], v170 offset:2048
	ds_read_b128 v[170:173], v170 offset:3072
	s_add_u32 s30, s30, 0xb0000
	s_addc_u32 s31, s31, 0
	s_mov_b32 m0, s52
	v_lshl_add_u64 v[222:223], s[30:31], 0, v[130:131]
	ds_read_b128 v[174:177], v141 offset:32768
	ds_read_b128 v[178:181], v141 offset:33792
	ds_read_b128 v[182:185], v141 offset:34816
	ds_read_b128 v[186:189], v141 offset:35840
	ds_read_b128 v[190:193], v141 offset:36864
	ds_read_b128 v[194:197], v141 offset:37888
	ds_read_b128 v[198:201], v141 offset:38912
	ds_read_b128 v[202:205], v141 offset:39936
	global_load_lds_dwordx4 v[222:223], off
	v_lshl_add_u64 v[222:223], s[30:31], 0, v[134:135]
	s_mov_b32 m0, s53
	s_nop 0
	global_load_lds_dwordx4 v[222:223], off
	s_waitcnt vmcnt(8)
	s_waitcnt lgkmcnt(0)
	s_barrier
	s_setprio 1
	v_mfma_f32_16x16x32_bf16 v[126:129], v[142:145], v[174:177], v[126:129]
	v_mfma_f32_16x16x32_bf16 v[126:129], v[146:149], v[178:181], v[126:129]
	v_mfma_f32_16x16x32_bf16 v[122:125], v[150:153], v[174:177], v[122:125]
	v_mfma_f32_16x16x32_bf16 v[122:125], v[154:157], v[178:181], v[122:125]
	v_mfma_f32_16x16x32_bf16 v[106:109], v[150:153], v[182:185], v[106:109]
	v_mfma_f32_16x16x32_bf16 v[106:109], v[154:157], v[186:189], v[106:109]
	v_mfma_f32_16x16x32_bf16 v[110:113], v[142:145], v[182:185], v[110:113]
	v_mfma_f32_16x16x32_bf16 v[110:113], v[146:149], v[186:189], v[110:113]
	v_mfma_f32_16x16x32_bf16 v[94:97], v[142:145], v[190:193], v[94:97]
	v_mfma_f32_16x16x32_bf16 v[94:97], v[146:149], v[194:197], v[94:97]
	v_mfma_f32_16x16x32_bf16 v[90:93], v[150:153], v[190:193], v[90:93]
	v_mfma_f32_16x16x32_bf16 v[90:93], v[154:157], v[194:197], v[90:93]
	v_mfma_f32_16x16x32_bf16 v[74:77], v[150:153], v[198:201], v[74:77]
	v_mfma_f32_16x16x32_bf16 v[74:77], v[154:157], v[202:205], v[74:77]
	v_mfma_f32_16x16x32_bf16 v[78:81], v[142:145], v[198:201], v[78:81]
	v_mfma_f32_16x16x32_bf16 v[78:81], v[146:149], v[202:205], v[78:81]
	v_mfma_f32_16x16x32_bf16 v[118:121], v[158:161], v[174:177], v[118:121]
	v_mfma_f32_16x16x32_bf16 v[118:121], v[162:165], v[178:181], v[118:121]
	v_mfma_f32_16x16x32_bf16 v[114:117], v[166:169], v[174:177], v[114:117]
	v_mfma_f32_16x16x32_bf16 v[114:117], v[170:173], v[178:181], v[114:117]
	v_mfma_f32_16x16x32_bf16 v[98:101], v[166:169], v[182:185], v[98:101]
	v_mfma_f32_16x16x32_bf16 v[98:101], v[170:173], v[186:189], v[98:101]
	v_mfma_f32_16x16x32_bf16 v[102:105], v[158:161], v[182:185], v[102:105]
	v_mfma_f32_16x16x32_bf16 v[102:105], v[162:165], v[186:189], v[102:105]
	v_mfma_f32_16x16x32_bf16 v[86:89], v[158:161], v[190:193], v[86:89]
	v_mfma_f32_16x16x32_bf16 v[86:89], v[162:165], v[194:197], v[86:89]
	v_mfma_f32_16x16x32_bf16 v[82:85], v[166:169], v[190:193], v[82:85]
	v_mfma_f32_16x16x32_bf16 v[82:85], v[170:173], v[194:197], v[82:85]
	s_setprio 2
	s_barrier
	v_mfma_f32_16x16x32_bf16 v[66:69], v[166:169], v[198:201], v[66:69]
	v_mfma_f32_16x16x32_bf16 v[66:69], v[170:173], v[202:205], v[66:69]
	v_mfma_f32_16x16x32_bf16 v[70:73], v[158:161], v[198:201], v[70:73]
	v_mfma_f32_16x16x32_bf16 v[70:73], v[162:165], v[202:205], v[70:73]
	s_setprio 0
	s_nop 0
	s_add_i32 s30, s59, s39
	v_lshl_add_u64 v[214:215], v[214:215], 0, s[24:25]
	s_mov_b32 m0, s30
	ds_read_b128 v[174:177], v141 offset:49152
	ds_read_b128 v[178:181], v141 offset:50176
	ds_read_b128 v[182:185], v141 offset:51200
	ds_read_b128 v[186:189], v141 offset:52224
	ds_read_b128 v[190:193], v141 offset:53248
	ds_read_b128 v[194:197], v141 offset:54272
	ds_read_b128 v[198:201], v141 offset:55296
	ds_read_b128 v[202:205], v141 offset:56320
	global_load_lds_dwordx4 v[214:215], off
	s_add_i32 m0, s30, 0x2000
	s_add_u32 s4, s4, 0xb0080
	v_lshl_add_u64 v[214:215], v[216:217], 0, s[24:25]
	s_addc_u32 s5, s5, 0
	s_add_i32 s30, s60, s39
	global_load_lds_dwordx4 v[214:215], off
	v_lshl_add_u64 v[214:215], s[4:5], 0, v[130:131]
	s_mov_b32 m0, s30
	s_nop 0
	global_load_lds_dwordx4 v[214:215], off
	v_lshl_add_u64 v[214:215], s[4:5], 0, v[134:135]
	s_add_i32 m0, s30, 0x2000
	s_nop 0
	global_load_lds_dwordx4 v[214:215], off
	v_lshl_add_u64 v[214:215], v[218:219], 0, s[24:25]
	s_mov_b32 m0, s54
	s_nop 0
	global_load_lds_dwordx4 v[214:215], off
	v_lshl_add_u64 v[214:215], v[220:221], 0, s[24:25]
	s_mov_b32 m0, s55
	s_nop 0
	global_load_lds_dwordx4 v[214:215], off
	s_waitcnt vmcnt(8)
	s_waitcnt lgkmcnt(0)
	s_barrier
	s_setprio 1
	v_mfma_f32_16x16x32_bf16 v[62:65], v[142:145], v[174:177], v[62:65]
	v_mfma_f32_16x16x32_bf16 v[62:65], v[146:149], v[178:181], v[62:65]
	v_mfma_f32_16x16x32_bf16 v[58:61], v[150:153], v[174:177], v[58:61]
	v_mfma_f32_16x16x32_bf16 v[58:61], v[154:157], v[178:181], v[58:61]
	v_mfma_f32_16x16x32_bf16 v[42:45], v[150:153], v[182:185], v[42:45]
	v_mfma_f32_16x16x32_bf16 v[42:45], v[154:157], v[186:189], v[42:45]
	v_mfma_f32_16x16x32_bf16 v[46:49], v[142:145], v[182:185], v[46:49]
	v_mfma_f32_16x16x32_bf16 v[46:49], v[146:149], v[186:189], v[46:49]
	v_mfma_f32_16x16x32_bf16 v[30:33], v[142:145], v[190:193], v[30:33]
	v_mfma_f32_16x16x32_bf16 v[30:33], v[146:149], v[194:197], v[30:33]
	v_mfma_f32_16x16x32_bf16 v[26:29], v[150:153], v[190:193], v[26:29]
	v_mfma_f32_16x16x32_bf16 v[26:29], v[154:157], v[194:197], v[26:29]
	v_mfma_f32_16x16x32_bf16 v[10:13], v[150:153], v[198:201], v[10:13]
	v_mfma_f32_16x16x32_bf16 v[10:13], v[154:157], v[202:205], v[10:13]
	v_mfma_f32_16x16x32_bf16 v[14:17], v[142:145], v[198:201], v[14:17]
	v_mfma_f32_16x16x32_bf16 v[14:17], v[146:149], v[202:205], v[14:17]
	v_mfma_f32_16x16x32_bf16 v[54:57], v[158:161], v[174:177], v[54:57]
	v_mfma_f32_16x16x32_bf16 v[54:57], v[162:165], v[178:181], v[54:57]
	v_mfma_f32_16x16x32_bf16 v[50:53], v[166:169], v[174:177], v[50:53]
	v_mfma_f32_16x16x32_bf16 v[50:53], v[170:173], v[178:181], v[50:53]
	v_mfma_f32_16x16x32_bf16 v[34:37], v[166:169], v[182:185], v[34:37]
	v_mfma_f32_16x16x32_bf16 v[34:37], v[170:173], v[186:189], v[34:37]
	v_mfma_f32_16x16x32_bf16 v[38:41], v[158:161], v[182:185], v[38:41]
	v_mfma_f32_16x16x32_bf16 v[38:41], v[162:165], v[186:189], v[38:41]
	v_mfma_f32_16x16x32_bf16 v[22:25], v[158:161], v[190:193], v[22:25]
	v_mfma_f32_16x16x32_bf16 v[22:25], v[162:165], v[194:197], v[22:25]
	v_mfma_f32_16x16x32_bf16 v[18:21], v[166:169], v[190:193], v[18:21]
	v_mfma_f32_16x16x32_bf16 v[18:21], v[170:173], v[194:197], v[18:21]
	s_setprio 2
	s_barrier
	v_mfma_f32_16x16x32_bf16 v[2:5], v[166:169], v[198:201], v[2:5]
	v_mfma_f32_16x16x32_bf16 v[2:5], v[170:173], v[202:205], v[2:5]
	v_mfma_f32_16x16x32_bf16 v[6:9], v[158:161], v[198:201], v[6:9]
	v_mfma_f32_16x16x32_bf16 v[6:9], v[162:165], v[202:205], v[6:9]
	s_setprio 0
	s_nop 0
	s_add_i32 s58, s58, 2
	s_add_u32 s56, s56, 0x100
	s_addc_u32 s57, s57, 0
	s_add_u32 s2, s2, 0x100
	s_addc_u32 s3, s3, 0
	v_lshl_add_u64 v[136:137], v[136:137], 0, s[28:29]
	s_cmp_lt_u32 s58, 42
	v_lshl_add_u64 v[138:139], v[138:139], 0, s[28:29]
.LBB0_1018:
	s_add_u32 s4, s70, s56
	s_addc_u32 s5, s71, s57
	s_add_u32 s59, s70, s2
	s_addc_u32 s60, s71, s3
	s_add_i32 s61, 0, 0x10000
	s_cmp_eq_u32 s58, 40
	s_cselect_b32 s31, s1, s5
	s_cselect_b32 s30, s0, s4
	s_cselect_b32 s5, s15, s60
	s_cselect_b32 s4, s14, s59
	s_add_i32 s59, 0, 0x14000
	v_add_u32_e32 v154, s61, v140
	v_add_u32_e32 v170, s59, v140
	ds_read_b128 v[142:145], v154
	ds_read_b128 v[146:149], v154 offset:1024
	ds_read_b128 v[150:153], v154 offset:2048
	ds_read_b128 v[154:157], v154 offset:3072
	ds_read_b128 v[158:161], v170
	ds_read_b128 v[162:165], v170 offset:1024
	ds_read_b128 v[166:169], v170 offset:2048
	ds_read_b128 v[170:173], v170 offset:3072
	v_lshl_add_u64 v[214:215], s[70:71], 0, v[136:137]
	s_add_i32 m0, s50, 0xc000
	ds_read_b128 v[174:177], v141
	ds_read_b128 v[178:181], v141 offset:1024
	ds_read_b128 v[182:185], v141 offset:2048
	ds_read_b128 v[186:189], v141 offset:3072
	ds_read_b128 v[190:193], v141 offset:4096
	ds_read_b128 v[194:197], v141 offset:5120
	ds_read_b128 v[198:201], v141 offset:6144
	ds_read_b128 v[202:205], v141 offset:7168
	global_load_lds_dwordx4 v[214:215], off
	v_lshl_add_u64 v[214:215], s[70:71], 0, v[138:139]
	s_add_i32 m0, s50, 0xe000
	s_nop 0
	global_load_lds_dwordx4 v[214:215], off
	s_waitcnt vmcnt(8)
	s_waitcnt lgkmcnt(0)
	s_barrier
	s_setprio 1
	v_mfma_f32_16x16x32_bf16 v[126:129], v[142:145], v[174:177], v[126:129]
	v_mfma_f32_16x16x32_bf16 v[126:129], v[146:149], v[178:181], v[126:129]
	v_mfma_f32_16x16x32_bf16 v[122:125], v[150:153], v[174:177], v[122:125]
	v_mfma_f32_16x16x32_bf16 v[122:125], v[154:157], v[178:181], v[122:125]
	v_mfma_f32_16x16x32_bf16 v[106:109], v[150:153], v[182:185], v[106:109]
	v_mfma_f32_16x16x32_bf16 v[106:109], v[154:157], v[186:189], v[106:109]
	v_mfma_f32_16x16x32_bf16 v[110:113], v[142:145], v[182:185], v[110:113]
	v_mfma_f32_16x16x32_bf16 v[110:113], v[146:149], v[186:189], v[110:113]
	v_mfma_f32_16x16x32_bf16 v[94:97], v[142:145], v[190:193], v[94:97]
	v_mfma_f32_16x16x32_bf16 v[94:97], v[146:149], v[194:197], v[94:97]
	v_mfma_f32_16x16x32_bf16 v[90:93], v[150:153], v[190:193], v[90:93]
	v_mfma_f32_16x16x32_bf16 v[90:93], v[154:157], v[194:197], v[90:93]
	v_mfma_f32_16x16x32_bf16 v[74:77], v[150:153], v[198:201], v[74:77]
	v_mfma_f32_16x16x32_bf16 v[74:77], v[154:157], v[202:205], v[74:77]
	v_mfma_f32_16x16x32_bf16 v[78:81], v[142:145], v[198:201], v[78:81]
	v_mfma_f32_16x16x32_bf16 v[78:81], v[146:149], v[202:205], v[78:81]
	v_mfma_f32_16x16x32_bf16 v[118:121], v[158:161], v[174:177], v[118:121]
	v_mfma_f32_16x16x32_bf16 v[118:121], v[162:165], v[178:181], v[118:121]
	v_mfma_f32_16x16x32_bf16 v[114:117], v[166:169], v[174:177], v[114:117]
	v_mfma_f32_16x16x32_bf16 v[114:117], v[170:173], v[178:181], v[114:117]
	v_mfma_f32_16x16x32_bf16 v[98:101], v[166:169], v[182:185], v[98:101]
	v_mfma_f32_16x16x32_bf16 v[98:101], v[170:173], v[186:189], v[98:101]
	v_mfma_f32_16x16x32_bf16 v[102:105], v[158:161], v[182:185], v[102:105]
	v_mfma_f32_16x16x32_bf16 v[102:105], v[162:165], v[186:189], v[102:105]
	v_mfma_f32_16x16x32_bf16 v[86:89], v[158:161], v[190:193], v[86:89]
	v_mfma_f32_16x16x32_bf16 v[86:89], v[162:165], v[194:197], v[86:89]
	v_mfma_f32_16x16x32_bf16 v[82:85], v[166:169], v[190:193], v[82:85]
	v_mfma_f32_16x16x32_bf16 v[82:85], v[170:173], v[194:197], v[82:85]
	s_setprio 2
	s_barrier
	v_mfma_f32_16x16x32_bf16 v[66:69], v[166:169], v[198:201], v[66:69]
	v_mfma_f32_16x16x32_bf16 v[66:69], v[170:173], v[202:205], v[66:69]
	v_mfma_f32_16x16x32_bf16 v[70:73], v[158:161], v[198:201], v[70:73]
	v_mfma_f32_16x16x32_bf16 v[70:73], v[162:165], v[202:205], v[70:73]
	s_setprio 0
	s_nop 0
	s_add_i32 s60, s61, s39
	v_lshl_add_u64 v[214:215], s[4:5], 0, v[130:131]
	s_mov_b32 m0, s60
	ds_read_b128 v[174:177], v141 offset:16384
	ds_read_b128 v[178:181], v141 offset:17408
	ds_read_b128 v[182:185], v141 offset:18432
	ds_read_b128 v[186:189], v141 offset:19456
	ds_read_b128 v[190:193], v141 offset:20480
	ds_read_b128 v[194:197], v141 offset:21504
	ds_read_b128 v[198:201], v141 offset:22528
	ds_read_b128 v[202:205], v141 offset:23552
	global_load_lds_dwordx4 v[214:215], off
	s_add_i32 m0, s60, 0x2000
	s_add_u32 s60, s4, 0xb0000
	v_lshl_add_u64 v[216:217], s[4:5], 0, v[134:135]
	s_addc_u32 s61, s5, 0
	s_add_i32 s59, s59, s39
	global_load_lds_dwordx4 v[216:217], off
	v_lshl_add_u64 v[218:219], s[60:61], 0, v[130:131]
	s_mov_b32 m0, s59
	v_lshl_add_u64 v[220:221], s[30:31], 0, v[134:135]
	global_load_lds_dwordx4 v[218:219], off
	v_lshl_add_u64 v[218:219], s[60:61], 0, v[134:135]
	s_add_i32 m0, s59, 0x2000
	s_nop 0
	global_load_lds_dwordx4 v[218:219], off
	v_lshl_add_u64 v[218:219], s[30:31], 0, v[130:131]
	s_mov_b32 m0, s50
	s_nop 0
	global_load_lds_dwordx4 v[218:219], off
	s_mov_b32 m0, s51
	s_nop 0
	global_load_lds_dwordx4 v[220:221], off
	s_waitcnt vmcnt(8)
	s_waitcnt lgkmcnt(0)
	s_barrier
	s_setprio 1
	v_mfma_f32_16x16x32_bf16 v[62:65], v[142:145], v[174:177], v[62:65]
	v_mfma_f32_16x16x32_bf16 v[62:65], v[146:149], v[178:181], v[62:65]
	v_mfma_f32_16x16x32_bf16 v[58:61], v[150:153], v[174:177], v[58:61]
	v_mfma_f32_16x16x32_bf16 v[58:61], v[154:157], v[178:181], v[58:61]
	v_mfma_f32_16x16x32_bf16 v[42:45], v[150:153], v[182:185], v[42:45]
	v_mfma_f32_16x16x32_bf16 v[42:45], v[154:157], v[186:189], v[42:45]
	v_mfma_f32_16x16x32_bf16 v[46:49], v[142:145], v[182:185], v[46:49]
	v_mfma_f32_16x16x32_bf16 v[46:49], v[146:149], v[186:189], v[46:49]
	v_mfma_f32_16x16x32_bf16 v[30:33], v[142:145], v[190:193], v[30:33]
	v_mfma_f32_16x16x32_bf16 v[30:33], v[146:149], v[194:197], v[30:33]
	v_mfma_f32_16x16x32_bf16 v[26:29], v[150:153], v[190:193], v[26:29]
	v_mfma_f32_16x16x32_bf16 v[26:29], v[154:157], v[194:197], v[26:29]
	v_mfma_f32_16x16x32_bf16 v[10:13], v[150:153], v[198:201], v[10:13]
	v_mfma_f32_16x16x32_bf16 v[10:13], v[154:157], v[202:205], v[10:13]
	v_mfma_f32_16x16x32_bf16 v[14:17], v[142:145], v[198:201], v[14:17]
	v_mfma_f32_16x16x32_bf16 v[14:17], v[146:149], v[202:205], v[14:17]
	v_mfma_f32_16x16x32_bf16 v[54:57], v[158:161], v[174:177], v[54:57]
	v_mfma_f32_16x16x32_bf16 v[54:57], v[162:165], v[178:181], v[54:57]
	v_mfma_f32_16x16x32_bf16 v[50:53], v[166:169], v[174:177], v[50:53]
	v_mfma_f32_16x16x32_bf16 v[50:53], v[170:173], v[178:181], v[50:53]
	v_mfma_f32_16x16x32_bf16 v[34:37], v[166:169], v[182:185], v[34:37]
	v_mfma_f32_16x16x32_bf16 v[34:37], v[170:173], v[186:189], v[34:37]
	v_mfma_f32_16x16x32_bf16 v[38:41], v[158:161], v[182:185], v[38:41]
	v_mfma_f32_16x16x32_bf16 v[38:41], v[162:165], v[186:189], v[38:41]
	v_mfma_f32_16x16x32_bf16 v[22:25], v[158:161], v[190:193], v[22:25]
	v_mfma_f32_16x16x32_bf16 v[22:25], v[162:165], v[194:197], v[22:25]
	v_mfma_f32_16x16x32_bf16 v[18:21], v[166:169], v[190:193], v[18:21]
	v_mfma_f32_16x16x32_bf16 v[18:21], v[170:173], v[194:197], v[18:21]
	s_setprio 2
	s_barrier
	v_mfma_f32_16x16x32_bf16 v[2:5], v[166:169], v[198:201], v[2:5]
	v_mfma_f32_16x16x32_bf16 v[2:5], v[170:173], v[202:205], v[2:5]
	v_mfma_f32_16x16x32_bf16 v[6:9], v[158:161], v[198:201], v[6:9]
	v_mfma_f32_16x16x32_bf16 v[6:9], v[162:165], v[202:205], v[6:9]
	s_setprio 0
	s_nop 0
	s_add_i32 s59, 0, 0x18000
	s_add_i32 s60, 0, 0x1c000
	v_add_u32_e32 v154, s59, v140
	v_add_u32_e32 v170, s60, v140
	ds_read_b128 v[142:145], v154
	ds_read_b128 v[146:149], v154 offset:1024
	ds_read_b128 v[150:153], v154 offset:2048
	ds_read_b128 v[154:157], v154 offset:3072
	ds_read_b128 v[158:161], v170
	ds_read_b128 v[162:165], v170 offset:1024
	ds_read_b128 v[166:169], v170 offset:2048
	ds_read_b128 v[170:173], v170 offset:3072
	s_add_u32 s30, s30, 0xb0000
	s_addc_u32 s31, s31, 0
	s_mov_b32 m0, s52
	v_lshl_add_u64 v[222:223], s[30:31], 0, v[130:131]
	ds_read_b128 v[174:177], v141 offset:32768
	ds_read_b128 v[178:181], v141 offset:33792
	ds_read_b128 v[182:185], v141 offset:34816
	ds_read_b128 v[186:189], v141 offset:35840
	ds_read_b128 v[190:193], v141 offset:36864
	ds_read_b128 v[194:197], v141 offset:37888
	ds_read_b128 v[198:201], v141 offset:38912
	ds_read_b128 v[202:205], v141 offset:39936
	global_load_lds_dwordx4 v[222:223], off
	v_lshl_add_u64 v[222:223], s[30:31], 0, v[134:135]
	s_mov_b32 m0, s53
	s_nop 0
	global_load_lds_dwordx4 v[222:223], off
	s_waitcnt vmcnt(8)
	s_waitcnt lgkmcnt(0)
	s_barrier
	s_setprio 1
	v_mfma_f32_16x16x32_bf16 v[126:129], v[142:145], v[174:177], v[126:129]
	v_mfma_f32_16x16x32_bf16 v[126:129], v[146:149], v[178:181], v[126:129]
	v_mfma_f32_16x16x32_bf16 v[122:125], v[150:153], v[174:177], v[122:125]
	v_mfma_f32_16x16x32_bf16 v[122:125], v[154:157], v[178:181], v[122:125]
	v_mfma_f32_16x16x32_bf16 v[106:109], v[150:153], v[182:185], v[106:109]
	v_mfma_f32_16x16x32_bf16 v[106:109], v[154:157], v[186:189], v[106:109]
	v_mfma_f32_16x16x32_bf16 v[110:113], v[142:145], v[182:185], v[110:113]
	v_mfma_f32_16x16x32_bf16 v[110:113], v[146:149], v[186:189], v[110:113]
	v_mfma_f32_16x16x32_bf16 v[94:97], v[142:145], v[190:193], v[94:97]
	v_mfma_f32_16x16x32_bf16 v[94:97], v[146:149], v[194:197], v[94:97]
	v_mfma_f32_16x16x32_bf16 v[90:93], v[150:153], v[190:193], v[90:93]
	v_mfma_f32_16x16x32_bf16 v[90:93], v[154:157], v[194:197], v[90:93]
	v_mfma_f32_16x16x32_bf16 v[74:77], v[150:153], v[198:201], v[74:77]
	v_mfma_f32_16x16x32_bf16 v[74:77], v[154:157], v[202:205], v[74:77]
	v_mfma_f32_16x16x32_bf16 v[78:81], v[142:145], v[198:201], v[78:81]
	v_mfma_f32_16x16x32_bf16 v[78:81], v[146:149], v[202:205], v[78:81]
	v_mfma_f32_16x16x32_bf16 v[118:121], v[158:161], v[174:177], v[118:121]
	v_mfma_f32_16x16x32_bf16 v[118:121], v[162:165], v[178:181], v[118:121]
	v_mfma_f32_16x16x32_bf16 v[114:117], v[166:169], v[174:177], v[114:117]
	v_mfma_f32_16x16x32_bf16 v[114:117], v[170:173], v[178:181], v[114:117]
	v_mfma_f32_16x16x32_bf16 v[98:101], v[166:169], v[182:185], v[98:101]
	v_mfma_f32_16x16x32_bf16 v[98:101], v[170:173], v[186:189], v[98:101]
	v_mfma_f32_16x16x32_bf16 v[102:105], v[158:161], v[182:185], v[102:105]
	v_mfma_f32_16x16x32_bf16 v[102:105], v[162:165], v[186:189], v[102:105]
	v_mfma_f32_16x16x32_bf16 v[86:89], v[158:161], v[190:193], v[86:89]
	v_mfma_f32_16x16x32_bf16 v[86:89], v[162:165], v[194:197], v[86:89]
	v_mfma_f32_16x16x32_bf16 v[82:85], v[166:169], v[190:193], v[82:85]
	v_mfma_f32_16x16x32_bf16 v[82:85], v[170:173], v[194:197], v[82:85]
	s_setprio 2
	s_barrier
	v_mfma_f32_16x16x32_bf16 v[66:69], v[166:169], v[198:201], v[66:69]
	v_mfma_f32_16x16x32_bf16 v[66:69], v[170:173], v[202:205], v[66:69]
	v_mfma_f32_16x16x32_bf16 v[70:73], v[158:161], v[198:201], v[70:73]
	v_mfma_f32_16x16x32_bf16 v[70:73], v[162:165], v[202:205], v[70:73]
	s_setprio 0
	s_nop 0
	s_add_i32 s30, s59, s39
	v_lshl_add_u64 v[214:215], v[214:215], 0, s[24:25]
	s_mov_b32 m0, s30
	ds_read_b128 v[174:177], v141 offset:49152
	ds_read_b128 v[178:181], v141 offset:50176
	ds_read_b128 v[182:185], v141 offset:51200
	ds_read_b128 v[186:189], v141 offset:52224
	ds_read_b128 v[190:193], v141 offset:53248
	ds_read_b128 v[194:197], v141 offset:54272
	ds_read_b128 v[198:201], v141 offset:55296
	ds_read_b128 v[202:205], v141 offset:56320
	global_load_lds_dwordx4 v[214:215], off
	s_add_i32 m0, s30, 0x2000
	s_add_u32 s4, s4, 0xb0080
	v_lshl_add_u64 v[214:215], v[216:217], 0, s[24:25]
	s_addc_u32 s5, s5, 0
	s_add_i32 s30, s60, s39
	global_load_lds_dwordx4 v[214:215], off
	v_lshl_add_u64 v[214:215], s[4:5], 0, v[130:131]
	s_mov_b32 m0, s30
	s_nop 0
	global_load_lds_dwordx4 v[214:215], off
	v_lshl_add_u64 v[214:215], s[4:5], 0, v[134:135]
	s_add_i32 m0, s30, 0x2000
	s_nop 0
	global_load_lds_dwordx4 v[214:215], off
	v_lshl_add_u64 v[214:215], v[218:219], 0, s[24:25]
	s_mov_b32 m0, s54
	s_nop 0
	global_load_lds_dwordx4 v[214:215], off
	v_lshl_add_u64 v[214:215], v[220:221], 0, s[24:25]
	s_mov_b32 m0, s55
	s_nop 0
	global_load_lds_dwordx4 v[214:215], off
	s_waitcnt vmcnt(8)
	s_waitcnt lgkmcnt(0)
	s_barrier
	s_setprio 1
	v_mfma_f32_16x16x32_bf16 v[62:65], v[142:145], v[174:177], v[62:65]
	v_mfma_f32_16x16x32_bf16 v[62:65], v[146:149], v[178:181], v[62:65]
	v_mfma_f32_16x16x32_bf16 v[58:61], v[150:153], v[174:177], v[58:61]
	v_mfma_f32_16x16x32_bf16 v[58:61], v[154:157], v[178:181], v[58:61]
	v_mfma_f32_16x16x32_bf16 v[42:45], v[150:153], v[182:185], v[42:45]
	v_mfma_f32_16x16x32_bf16 v[42:45], v[154:157], v[186:189], v[42:45]
	v_mfma_f32_16x16x32_bf16 v[46:49], v[142:145], v[182:185], v[46:49]
	v_mfma_f32_16x16x32_bf16 v[46:49], v[146:149], v[186:189], v[46:49]
	v_mfma_f32_16x16x32_bf16 v[30:33], v[142:145], v[190:193], v[30:33]
	v_mfma_f32_16x16x32_bf16 v[30:33], v[146:149], v[194:197], v[30:33]
	v_mfma_f32_16x16x32_bf16 v[26:29], v[150:153], v[190:193], v[26:29]
	v_mfma_f32_16x16x32_bf16 v[26:29], v[154:157], v[194:197], v[26:29]
	v_mfma_f32_16x16x32_bf16 v[10:13], v[150:153], v[198:201], v[10:13]
	v_mfma_f32_16x16x32_bf16 v[10:13], v[154:157], v[202:205], v[10:13]
	v_mfma_f32_16x16x32_bf16 v[14:17], v[142:145], v[198:201], v[14:17]
	v_mfma_f32_16x16x32_bf16 v[14:17], v[146:149], v[202:205], v[14:17]
	v_mfma_f32_16x16x32_bf16 v[54:57], v[158:161], v[174:177], v[54:57]
	v_mfma_f32_16x16x32_bf16 v[54:57], v[162:165], v[178:181], v[54:57]
	v_mfma_f32_16x16x32_bf16 v[50:53], v[166:169], v[174:177], v[50:53]
	v_mfma_f32_16x16x32_bf16 v[50:53], v[170:173], v[178:181], v[50:53]
	v_mfma_f32_16x16x32_bf16 v[34:37], v[166:169], v[182:185], v[34:37]
	v_mfma_f32_16x16x32_bf16 v[34:37], v[170:173], v[186:189], v[34:37]
	v_mfma_f32_16x16x32_bf16 v[38:41], v[158:161], v[182:185], v[38:41]
	v_mfma_f32_16x16x32_bf16 v[38:41], v[162:165], v[186:189], v[38:41]
	v_mfma_f32_16x16x32_bf16 v[22:25], v[158:161], v[190:193], v[22:25]
	v_mfma_f32_16x16x32_bf16 v[22:25], v[162:165], v[194:197], v[22:25]
	v_mfma_f32_16x16x32_bf16 v[18:21], v[166:169], v[190:193], v[18:21]
	v_mfma_f32_16x16x32_bf16 v[18:21], v[170:173], v[194:197], v[18:21]
	s_setprio 2
	s_barrier
	v_mfma_f32_16x16x32_bf16 v[2:5], v[166:169], v[198:201], v[2:5]
	v_mfma_f32_16x16x32_bf16 v[2:5], v[170:173], v[202:205], v[2:5]
	v_mfma_f32_16x16x32_bf16 v[6:9], v[158:161], v[198:201], v[6:9]
	v_mfma_f32_16x16x32_bf16 v[6:9], v[162:165], v[202:205], v[6:9]
	s_setprio 0
	s_nop 0
	s_add_i32 s58, s58, 2
	s_add_u32 s56, s56, 0x100
	s_addc_u32 s57, s57, 0
	s_add_u32 s2, s2, 0x100
	s_addc_u32 s3, s3, 0
	v_lshl_add_u64 v[136:137], v[136:137], 0, s[28:29]
	s_cmp_lt_u32 s58, 42
	v_lshl_add_u64 v[138:139], v[138:139], 0, s[28:29]
	s_cbranch_scc1 .LBB0_1018
	s_waitcnt vmcnt(0)
	s_cmpk_gt_u32 s36, 0xff
	s_cbranch_scc1 .LBB0_1021
	s_barrier
